# phase 0: transposed LDS reads batched, silu table loads unrolled, modulation units with all w_ada loads up front; grid barrier polls the cross-XCC generation word
# speedup vs baseline: 1.0060x; 1.0060x over previous
; DI float silu_f(float x) { return x * __builtin_amdgcn_rcpf(1.0f + __expf(-x)); }
; DI void phase0(const Params& p, unsigned char* shm, int tid) {
;     ...
;   for (int i = tid; i < 4096; i += NTHR) ssc[i] = silu_f(p.c[i]);
.LBB0_4:
	s_mov_b64 s[6:7], 0x1000
	global_load_dword v100, v[2:3], off
	global_load_dword v101, v[2:3], off offset:2048
	v_lshl_add_u64 v[108:109], v[2:3], 0, s[6:7]
	global_load_dword v102, v[108:109], off
	global_load_dword v103, v[108:109], off offset:2048
	v_lshl_add_u64 v[108:109], v[108:109], 0, s[6:7]
	global_load_dword v104, v[108:109], off
	global_load_dword v105, v[108:109], off offset:2048
	v_lshl_add_u64 v[108:109], v[108:109], 0, s[6:7]
	global_load_dword v106, v[108:109], off
	global_load_dword v107, v[108:109], off offset:2048
	s_waitcnt vmcnt(7)
	v_mul_f32_e32 v8, 0xbfb8aa3b, v100
	v_exp_f32_e32 v8, v8
	s_nop 0
	v_add_f32_e32 v8, 1.0, v8
	v_rcp_f32_e32 v8, v8
	s_nop 0
	v_mul_f32_e32 v5, v100, v8
	ds_write_b32 v7, v5
	s_waitcnt vmcnt(6)
	v_mul_f32_e32 v8, 0xbfb8aa3b, v101
	v_exp_f32_e32 v8, v8
	s_nop 0
	v_add_f32_e32 v8, 1.0, v8
	v_rcp_f32_e32 v8, v8
	s_nop 0
	v_mul_f32_e32 v5, v101, v8
	ds_write_b32 v7, v5 offset:2048
	s_waitcnt vmcnt(5)
	v_mul_f32_e32 v8, 0xbfb8aa3b, v102
	v_exp_f32_e32 v8, v8
	s_nop 0
	v_add_f32_e32 v8, 1.0, v8
	v_rcp_f32_e32 v8, v8
	s_nop 0
	v_mul_f32_e32 v5, v102, v8
	ds_write_b32 v7, v5 offset:4096
	s_waitcnt vmcnt(4)
	v_mul_f32_e32 v8, 0xbfb8aa3b, v103
	v_exp_f32_e32 v8, v8
	s_nop 0
	v_add_f32_e32 v8, 1.0, v8
	v_rcp_f32_e32 v8, v8
	s_nop 0
	v_mul_f32_e32 v5, v103, v8
	ds_write_b32 v7, v5 offset:6144
	s_waitcnt vmcnt(3)
	v_mul_f32_e32 v8, 0xbfb8aa3b, v104
	v_exp_f32_e32 v8, v8
	s_nop 0
	v_add_f32_e32 v8, 1.0, v8
	v_rcp_f32_e32 v8, v8
	s_nop 0
	v_mul_f32_e32 v5, v104, v8
	ds_write_b32 v7, v5 offset:8192
	s_waitcnt vmcnt(2)
	v_mul_f32_e32 v8, 0xbfb8aa3b, v105
	v_exp_f32_e32 v8, v8
	s_nop 0
	v_add_f32_e32 v8, 1.0, v8
	v_rcp_f32_e32 v8, v8
	s_nop 0
	v_mul_f32_e32 v5, v105, v8
	ds_write_b32 v7, v5 offset:10240
	s_waitcnt vmcnt(1)
	v_mul_f32_e32 v8, 0xbfb8aa3b, v106
	v_exp_f32_e32 v8, v8
	s_nop 0
	v_add_f32_e32 v8, 1.0, v8
	v_rcp_f32_e32 v8, v8
	s_nop 0
	v_mul_f32_e32 v5, v106, v8
	ds_write_b32 v7, v5 offset:12288
	s_waitcnt vmcnt(0)
	v_mul_f32_e32 v8, 0xbfb8aa3b, v107
	v_exp_f32_e32 v8, v8
	s_nop 0
	v_add_f32_e32 v8, 1.0, v8
	v_rcp_f32_e32 v8, v8
	s_nop 0
	v_mul_f32_e32 v5, v107, v8
	ds_write_b32 v7, v5 offset:14336

; DI unsigned pk2(float lo, float hi) { unsigned r; asm volatile("v_cvt_pk_bf16_f32 %0, %1, %2" : "=v"(r) : "v"(lo), "v"(hi)); return r; }
; DI void transpose_tile(const float* src, int src_ld, int k0, int sc0, bf16_t* dst, int dst_ld, int n0, float* sT  , int tid) {
;     ...
;   for (int i = 0; i < 8; ++i) v[i] = *(const float4*)(src + (size_t)(k0 + (tid >> 6) + 8 * i) * src_ld + sc0 + (tid & 63) * 4);
; #pragma unroll
;   for (int i = 0; i < 8; ++i) { float* q = sT + ((tid >> 6) + 8 * i) * 257 + (tid & 63) * 4; q[0] = v[i].x; q[1] = v[i].y; q[2] = v[i].z; q[3] = v[i].w; }
;   __syncthreads();
;   {
;     const int n = tid >> 1, kh = (tid & 1) * 32;
; #pragma unroll
;     for (int q = 0; q < 4; ++q) {
;       const float* c = sT + (kh + 8 * q) * 257 + n;
;       uint4 w;
;       w.x = pk2(c[0], c[257]); w.y = pk2(c[2 * 257], c[3 * 257]); w.z = pk2(c[4 * 257], c[5 * 257]); w.w = pk2(c[6 * 257], c[7 * 257]);
;       *(uint4*)(dst + wimg_off(n0 + n, k0 + kh + 8 * q, dst_ld)) = w;
;     }
;   }
;   __syncthreads();
; DI void phase0(const Params& p, unsigned char* shm, int tid) {
;     ...
;       const int j = it - n_mod - n_win, l = j / 128, r = j % 128, kt = r / 4, nt = r % 4;
;       transpose_tile(p.w_out + (size_t)l * 2048 * 1024, 1024, kt * 64, nt * 256, wtout + (size_t)l * 1024 * 2048, 2048, nt * 256, sT, tid);
.LBB0_11:
	s_cmpk_gt_u32 s27, 0x73f
	s_cbranch_scc0 .LBB0_13
	s_add_i32 s10, s27, 0xfffff8c0
	s_lshr_b32 s6, s10, 7
	v_readlane_b32 s40, v252, 24
	s_lshl_b64 s[4:5], s[6:7], 23
	v_readlane_b32 s52, v252, 36
	v_readlane_b32 s53, v252, 37
	s_add_u32 s11, s52, s4
	s_addc_u32 s28, s53, s5
	s_lshl_b32 s4, s10, 4
	s_and_b32 s29, s4, 0x7c0
	s_lshl_b32 s4, s27, 8
	s_and_b32 s30, s4, 0x300
	s_lshl_b64 s[4:5], s[6:7], 22
	v_readlane_b32 s6, v252, 20
	s_add_u32 s4, s6, s4
	v_readlane_b32 s6, v252, 21
	s_addc_u32 s5, s6, s5
	s_lshl_b32 s6, s30, 2
	v_add_u32_e32 v10, s29, v3
	s_add_u32 s10, s11, s6
	s_addc_u32 s11, s28, 0
	v_ashrrev_i32_e32 v11, 31, v10
	v_lshl_add_u64 v[12:13], s[10:11], 0, v[6:7]
	v_lshlrev_b64 v[10:11], 12, v[10:11]
	v_lshl_add_u64 v[14:15], v[12:13], 0, v[10:11]
	v_add_co_u32_e32 v36, vcc, s13, v14
	v_readlane_b32 s41, v252, 25
	s_nop 0
	v_addc_co_u32_e32 v37, vcc, 0, v15, vcc
	v_add_co_u32_e32 v40, vcc, s14, v14
	global_load_dwordx4 v[10:13], v[14:15], off
	s_nop 0
	global_load_dwordx4 v[36:39], v[36:37], off
	v_addc_co_u32_e32 v41, vcc, 0, v15, vcc
	v_add_co_u32_e32 v44, vcc, s15, v14
	v_readlane_b32 s42, v252, 26
	s_nop 0
	v_addc_co_u32_e32 v45, vcc, 0, v15, vcc
	v_add_co_u32_e32 v48, vcc, s16, v14
	global_load_dwordx4 v[40:43], v[40:41], off
	s_nop 0
	global_load_dwordx4 v[44:47], v[44:45], off
	v_addc_co_u32_e32 v49, vcc, 0, v15, vcc
	v_add_co_u32_e32 v52, vcc, s17, v14
	v_readlane_b32 s43, v252, 27
	s_nop 0
	v_addc_co_u32_e32 v53, vcc, 0, v15, vcc
	global_load_dwordx4 v[48:51], v[48:49], off
	s_nop 0
	global_load_dwordx4 v[52:55], v[52:53], off
	v_add_co_u32_e32 v56, vcc, s18, v14
	v_readlane_b32 s44, v252, 28
	s_nop 0
	v_addc_co_u32_e32 v57, vcc, 0, v15, vcc
	global_load_dwordx4 v[56:59], v[56:57], off
	v_add_co_u32_e32 v14, vcc, s19, v14
	v_readlane_b32 s45, v252, 29
	s_nop 0
	v_addc_co_u32_e32 v15, vcc, 0, v15, vcc
	global_load_dwordx4 v[60:63], v[14:15], off
	v_or_b32_e32 v14, s29, v16
	v_mov_b32_e32 v15, v7
	v_readlane_b32 s46, v252, 30
	v_readlane_b32 s47, v252, 31
	v_readlane_b32 s48, v252, 32
	v_readlane_b32 s49, v252, 33
	v_readlane_b32 s50, v252, 34
	v_readlane_b32 s51, v252, 35
	v_readlane_b32 s54, v252, 38
	v_readlane_b32 s55, v252, 39
	s_waitcnt vmcnt(7)
	ds_write2_b32 v20, v10, v11 offset1:1
	ds_write2_b32 v20, v12, v13 offset0:2 offset1:3
	s_waitcnt vmcnt(6)
	ds_write2_b32 v21, v36, v37 offset1:1
	ds_write2_b32 v22, v38, v39 offset1:1
	s_waitcnt vmcnt(5)
	ds_write2_b32 v23, v40, v41 offset1:1
	ds_write2_b32 v24, v42, v43 offset1:1
	s_waitcnt vmcnt(4)
	ds_write2_b32 v25, v44, v45 offset1:1
	ds_write2_b32 v26, v46, v47 offset1:1
	s_waitcnt vmcnt(3)
	ds_write2_b32 v27, v48, v49 offset1:1
	ds_write2_b32 v28, v50, v51 offset1:1
	s_waitcnt vmcnt(2)
	ds_write2_b32 v29, v52, v53 offset1:1
	ds_write2_b32 v30, v54, v55 offset1:1
	s_waitcnt vmcnt(1)
	ds_write2_b32 v31, v56, v57 offset1:1
	ds_write2_b32 v32, v58, v59 offset1:1
	s_waitcnt vmcnt(0)
	ds_write2_b32 v33, v60, v61 offset1:1
	ds_write2_b32 v34, v62, v63 offset1:1
	s_waitcnt lgkmcnt(0)
	s_barrier
	ds_read_b32 v100, v35 offset:1028
	ds_read_b32 v101, v35
	ds_read_b32 v102, v35 offset:3084
	ds_read_b32 v103, v35 offset:2056
	ds_read_b32 v104, v35 offset:5140
	ds_read_b32 v105, v35 offset:4112
	ds_read_b32 v106, v35 offset:7196
	ds_read_b32 v107, v35 offset:6168
	ds_read_b32 v108, v35 offset:9252
	ds_read_b32 v109, v35 offset:8224
	ds_read_b32 v110, v35 offset:11308
	ds_read_b32 v111, v35 offset:10280
	ds_read_b32 v112, v35 offset:13364
	ds_read_b32 v113, v35 offset:12336
	ds_read_b32 v114, v35 offset:15420
	ds_read_b32 v115, v35 offset:14392
	ds_read_b32 v116, v35 offset:17476
	ds_read_b32 v117, v35 offset:16448
	ds_read_b32 v118, v35 offset:19532
	ds_read_b32 v119, v35 offset:18504
	ds_read_b32 v120, v35 offset:21588
	ds_read_b32 v121, v35 offset:20560
	ds_read_b32 v122, v35 offset:23644
	ds_read_b32 v123, v35 offset:22616
	ds_read_b32 v124, v35 offset:25700
	ds_read_b32 v125, v35 offset:24672
	ds_read_b32 v126, v35 offset:27756
	ds_read_b32 v127, v35 offset:26728
	ds_read_b32 v128, v35 offset:29812
	ds_read_b32 v129, v35 offset:28784
	ds_read_b32 v130, v35 offset:31868
	ds_read_b32 v131, v35 offset:30840
	s_waitcnt lgkmcnt(0)
	v_cvt_pk_bf16_f32 v10, v101, v100
	v_cvt_pk_bf16_f32 v11, v103, v102
	v_add_u32_e32 v13, s30, v5
	v_lshlrev_b32_e32 v40, 6, v13
	v_ashrrev_i32_e32 v38, 7, v13
	v_lshlrev_b32_e32 v41, 2, v13
	v_cvt_pk_bf16_f32 v12, v105, v104
	v_ashrrev_i32_e32 v39, 31, v38
	v_cvt_pk_bf16_f32 v13, v107, v106
	v_lshlrev_b64 v[38:39], 19, v[38:39]
	v_mov_b32_e32 v37, v7
	v_lshlrev_b32_e32 v36, 8, v14
	v_and_b32_e32 v43, 32, v41
	v_lshl_add_u64 v[38:39], s[4:5], 0, v[38:39]
	v_and_or_b32 v14, v40, s20, v43
	v_lshl_add_u64 v[36:37], v[38:39], 0, v[36:37]
	v_lshl_add_u64 v[14:15], v[36:37], 0, v[14:15]
	global_store_dwordx4 v[14:15], v[10:13], off
	s_mov_b64 s[4:5], 0
	v_cvt_pk_bf16_f32 v10, v109, v108
	v_cvt_pk_bf16_f32 v11, v111, v110
	v_cvt_pk_bf16_f32 v12, v113, v112
	v_cvt_pk_bf16_f32 v13, v115, v114
	global_store_dwordx4 v[14:15], v[10:13], off offset:16
	v_mov_b32_e32 v15, v7
	v_cvt_pk_bf16_f32 v10, v117, v116
	v_cvt_pk_bf16_f32 v11, v119, v118
	v_cvt_pk_bf16_f32 v12, v121, v120
	v_and_b32_e32 v38, 0x3c0, v40
	v_and_b32_e32 v39, 0x1c00, v40
	v_cvt_pk_bf16_f32 v13, v123, v122
	v_bitop3_b32 v14, v38, v41, 32 bitop3:0x72
	v_or_b32_e32 v14, v14, v39
	v_lshl_add_u64 v[14:15], v[36:37], 0, v[14:15]
	global_store_dwordx4 v[14:15], v[10:13], off
	v_bitop3_b32 v14, v38, v43, 48 bitop3:0x36
	v_mov_b32_e32 v15, v7
	v_cvt_pk_bf16_f32 v10, v125, v124
	v_cvt_pk_bf16_f32 v11, v127, v126
	v_cvt_pk_bf16_f32 v12, v129, v128
	v_or_b32_e32 v14, v14, v39
	v_lshl_add_u64 v[14:15], v[36:37], 0, v[14:15]
	v_cvt_pk_bf16_f32 v13, v131, v130
	global_store_dwordx4 v[14:15], v[10:13], off
	s_barrier

; DI unsigned pk2(float lo, float hi) { unsigned r; asm volatile("v_cvt_pk_bf16_f32 %0, %1, %2" : "=v"(r) : "v"(lo), "v"(hi)); return r; }
; DI void transpose_tile(const float* src, int src_ld, int k0, int sc0, bf16_t* dst, int dst_ld, int n0, float* sT  , int tid) {
;     ...
;   for (int i = 0; i < 8; ++i) v[i] = *(const float4*)(src + (size_t)(k0 + (tid >> 6) + 8 * i) * src_ld + sc0 + (tid & 63) * 4);
; #pragma unroll
;   for (int i = 0; i < 8; ++i) { float* q = sT + ((tid >> 6) + 8 * i) * 257 + (tid & 63) * 4; q[0] = v[i].x; q[1] = v[i].y; q[2] = v[i].z; q[3] = v[i].w; }
;   __syncthreads();
;   {
;     const int n = tid >> 1, kh = (tid & 1) * 32;
; #pragma unroll
;     for (int q = 0; q < 4; ++q) {
;       const float* c = sT + (kh + 8 * q) * 257 + n;
;       uint4 w;
;       w.x = pk2(c[0], c[257]); w.y = pk2(c[2 * 257], c[3 * 257]); w.z = pk2(c[4 * 257], c[5 * 257]); w.w = pk2(c[6 * 257], c[7 * 257]);
;       *(uint4*)(dst + wimg_off(n0 + n, k0 + kh + 8 * q, dst_ld)) = w;
;     }
;   }
;   __syncthreads();
; DI void phase0(const Params& p, unsigned char* shm, int tid) {
;     ...
;       const int j = it - n_mod, l = j / (16 * 26), r = j % (16 * 26), kt = r / 26, nt = r % 26;
;       transpose_tile(p.w_in + (size_t)l * 1024 * NIN, NIN, kt * 64, win_src_col(nt * 256), wtin + (size_t)l * NWIN * 1024, 1024, nt * 256, sT, tid);
.LBB0_31:
	s_and_b32 s4, 0xffff, s11
	v_readlane_b32 s40, v252, 2
	s_mul_hi_u32 s5, s4, 0x1a18000
	s_mul_i32 s4, s4, 0x1a18000
	v_readlane_b32 s52, v252, 14
	v_readlane_b32 s53, v252, 15
	s_add_u32 s30, s52, s4
	s_addc_u32 s31, s53, s5
	s_lshl_b32 s4, s28, 6
	s_and_b32 s33, s4, 0xffc0
	s_mul_i32 s11, s11, 0xd80000
	v_readlane_b32 s4, v252, 18
	v_readlane_b32 s5, v252, 19
	s_add_u32 s4, s4, s11
	s_addc_u32 s5, s5, 0
	s_lshl_b64 s[28:29], s[6:7], 2
	s_add_u32 s28, s30, s28
	v_add_u32_e32 v54, s33, v3
	s_addc_u32 s29, s31, s29
	v_lshl_add_u64 v[14:15], s[28:29], 0, v[6:7]
	v_add_u32_e32 v12, 8, v54
	v_mad_i64_i32 v[36:37], s[28:29], v12, s21, v[14:15]
	v_add_u32_e32 v12, 16, v54
	v_mad_i64_i32 v[40:41], s[28:29], v12, s21, v[14:15]
	v_add_u32_e32 v12, 24, v54
	v_mad_i64_i32 v[44:45], s[28:29], v12, s21, v[14:15]
	v_add_u32_e32 v12, 32, v54
	v_add_u32_e32 v38, 40, v54
	v_add_u32_e32 v50, 48, v54
	v_mad_i64_i32 v[10:11], s[28:29], v54, s21, v[14:15]
	v_mad_i64_i32 v[48:49], s[28:29], v12, s21, v[14:15]
	v_mad_i64_i32 v[52:53], s[28:29], v38, s21, v[14:15]
	v_mad_i64_i32 v[56:57], s[28:29], v50, s21, v[14:15]
	global_load_dwordx4 v[10:13], v[10:11], off
	v_add_u32_e32 v60, 56, v54
	global_load_dwordx4 v[36:39], v[36:37], off
	s_nop 0
	global_load_dwordx4 v[40:43], v[40:41], off
	s_nop 0
	global_load_dwordx4 v[44:47], v[44:45], off
	v_mad_i64_i32 v[14:15], s[28:29], v60, s21, v[14:15]
	global_load_dwordx4 v[48:51], v[48:49], off
	s_nop 0
	global_load_dwordx4 v[52:55], v[52:53], off
	s_nop 0
	global_load_dwordx4 v[56:59], v[56:57], off
	v_readlane_b32 s41, v252, 3
	global_load_dwordx4 v[60:63], v[14:15], off
	v_mov_b32_e32 v15, v7
	v_readlane_b32 s42, v252, 4
	v_readlane_b32 s43, v252, 5
	v_readlane_b32 s44, v252, 6
	v_readlane_b32 s45, v252, 7
	v_readlane_b32 s46, v252, 8
	v_readlane_b32 s47, v252, 9
	v_readlane_b32 s48, v252, 10
	v_readlane_b32 s49, v252, 11
	v_readlane_b32 s50, v252, 12
	v_readlane_b32 s51, v252, 13
	v_readlane_b32 s54, v252, 16
	v_readlane_b32 s55, v252, 17
	s_waitcnt vmcnt(7)
	ds_write2_b32 v20, v10, v11 offset1:1
	ds_write2_b32 v20, v12, v13 offset0:2 offset1:3
	s_waitcnt vmcnt(6)
	ds_write2_b32 v21, v36, v37 offset1:1
	ds_write2_b32 v22, v38, v39 offset1:1
	s_waitcnt vmcnt(5)
	ds_write2_b32 v23, v40, v41 offset1:1
	ds_write2_b32 v24, v42, v43 offset1:1
	s_waitcnt vmcnt(4)
	ds_write2_b32 v25, v44, v45 offset1:1
	ds_write2_b32 v26, v46, v47 offset1:1
	s_waitcnt vmcnt(3)
	ds_write2_b32 v27, v48, v49 offset1:1
	ds_write2_b32 v28, v50, v51 offset1:1
	s_waitcnt vmcnt(2)
	ds_write2_b32 v29, v52, v53 offset1:1
	ds_write2_b32 v30, v54, v55 offset1:1
	s_waitcnt vmcnt(1)
	ds_write2_b32 v31, v56, v57 offset1:1
	ds_write2_b32 v32, v58, v59 offset1:1
	s_waitcnt vmcnt(0)
	ds_write2_b32 v33, v60, v61 offset1:1
	ds_write2_b32 v34, v62, v63 offset1:1
	s_waitcnt lgkmcnt(0)
	s_barrier
	ds_read_b32 v100, v35 offset:1028
	ds_read_b32 v101, v35
	ds_read_b32 v102, v35 offset:3084
	ds_read_b32 v103, v35 offset:2056
	ds_read_b32 v104, v35 offset:5140
	ds_read_b32 v105, v35 offset:4112
	ds_read_b32 v106, v35 offset:7196
	ds_read_b32 v107, v35 offset:6168
	ds_read_b32 v108, v35 offset:9252
	ds_read_b32 v109, v35 offset:8224
	ds_read_b32 v110, v35 offset:11308
	ds_read_b32 v111, v35 offset:10280
	ds_read_b32 v112, v35 offset:13364
	ds_read_b32 v113, v35 offset:12336
	ds_read_b32 v114, v35 offset:15420
	ds_read_b32 v115, v35 offset:14392
	ds_read_b32 v116, v35 offset:17476
	ds_read_b32 v117, v35 offset:16448
	ds_read_b32 v118, v35 offset:19532
	ds_read_b32 v119, v35 offset:18504
	ds_read_b32 v120, v35 offset:21588
	ds_read_b32 v121, v35 offset:20560
	ds_read_b32 v122, v35 offset:23644
	ds_read_b32 v123, v35 offset:22616
	ds_read_b32 v124, v35 offset:25700
	ds_read_b32 v125, v35 offset:24672
	ds_read_b32 v126, v35 offset:27756
	ds_read_b32 v127, v35 offset:26728
	ds_read_b32 v128, v35 offset:29812
	ds_read_b32 v129, v35 offset:28784
	ds_read_b32 v130, v35 offset:31868
	ds_read_b32 v131, v35 offset:30840
	s_waitcnt lgkmcnt(0)
	v_cvt_pk_bf16_f32 v10, v101, v100
	v_cvt_pk_bf16_f32 v11, v103, v102
	v_add_u32_e32 v13, s10, v5
	v_lshlrev_b32_e32 v40, 6, v13
	v_ashrrev_i32_e32 v38, 7, v13
	v_lshlrev_b32_e32 v41, 2, v13
	v_cvt_pk_bf16_f32 v12, v105, v104
	v_ashrrev_i32_e32 v39, 31, v38
	v_cvt_pk_bf16_f32 v13, v107, v106
	v_lshlrev_b64 v[38:39], 18, v[38:39]
	v_or_b32_e32 v36, s33, v16
	v_mov_b32_e32 v37, v7
	v_and_b32_e32 v42, 32, v41
	v_lshlrev_b32_e32 v36, 8, v36
	v_lshl_add_u64 v[38:39], s[4:5], 0, v[38:39]
	v_and_or_b32 v14, v40, s20, v42
	v_lshl_add_u64 v[36:37], v[38:39], 0, v[36:37]
	v_lshl_add_u64 v[14:15], v[36:37], 0, v[14:15]
	global_store_dwordx4 v[14:15], v[10:13], off
	s_nop 0
	v_cvt_pk_bf16_f32 v10, v109, v108
	v_cvt_pk_bf16_f32 v11, v111, v110
	v_cvt_pk_bf16_f32 v12, v113, v112
	v_cvt_pk_bf16_f32 v13, v115, v114
	global_store_dwordx4 v[14:15], v[10:13], off offset:16
	v_mov_b32_e32 v15, v7
	v_cvt_pk_bf16_f32 v10, v117, v116
	v_cvt_pk_bf16_f32 v11, v119, v118
	v_cvt_pk_bf16_f32 v12, v121, v120
	v_and_b32_e32 v38, 0x3c0, v40
	v_and_b32_e32 v39, 0x1c00, v40
	v_cvt_pk_bf16_f32 v13, v123, v122
	v_bitop3_b32 v14, v38, v41, 32 bitop3:0x72
	v_or_b32_e32 v14, v14, v39
	v_lshl_add_u64 v[14:15], v[36:37], 0, v[14:15]
	global_store_dwordx4 v[14:15], v[10:13], off
	v_bitop3_b32 v14, v38, v42, 48 bitop3:0x36
	v_mov_b32_e32 v15, v7
	v_cvt_pk_bf16_f32 v10, v125, v124
	v_cvt_pk_bf16_f32 v11, v127, v126
	v_cvt_pk_bf16_f32 v12, v129, v128
	v_or_b32_e32 v14, v14, v39
	v_lshl_add_u64 v[14:15], v[36:37], 0, v[14:15]
	v_cvt_pk_bf16_f32 v13, v131, v130
	global_store_dwordx4 v[14:15], v[10:13], off
	s_barrier

; DI void phase0(const Params& p, unsigned char* shm, int tid) {
;     ...
;       const int l = it / 48, cgp = it % 48, kc = tid >> 6, col = tid & 63;
;       float a0 = 0.f, a1 = 0.f, a2 = 0.f, a3 = 0.f;
;       const float* wp = p.w_ada + ((size_t)l * 1024 + kc * 128) * 3072 + cgp * 64 + col;
; #pragma unroll 8
;       for (int k = 0; k < 128; ++k) {
;         const float w = wp[(size_t)k * 3072]; const int kk = kc * 128 + k;
;         a0 += ssc[kk] * w; a1 += ssc[1024 + kk] * w; a2 += ssc[2048 + kk] * w; a3 += ssc[3072 + kk] * w;
.LBB0_34:
	v_readfirstlane_b32 s4, v10
	v_readfirstlane_b32 s5, v11
	v_lshlrev_b32_e32 v86, 2, v2
	s_nop 1
	s_sub_u32 s4, s4, 0xc000
	s_subb_u32 s5, s5, 0
	global_load_dword v100, v86, s[4:5]
	s_add_u32 s4, s4, 0x3000
	s_addc_u32 s5, s5, 0
	global_load_dword v101, v86, s[4:5]
	s_add_u32 s4, s4, 0x3000
	s_addc_u32 s5, s5, 0
	global_load_dword v102, v86, s[4:5]
	s_add_u32 s4, s4, 0x3000
	s_addc_u32 s5, s5, 0
	global_load_dword v103, v86, s[4:5]
	s_add_u32 s4, s4, 0x3000
	s_addc_u32 s5, s5, 0
	global_load_dword v104, v86, s[4:5]
	s_add_u32 s4, s4, 0x3000
	s_addc_u32 s5, s5, 0
	global_load_dword v105, v86, s[4:5]
	s_add_u32 s4, s4, 0x3000
	s_addc_u32 s5, s5, 0
	global_load_dword v106, v86, s[4:5]
	s_add_u32 s4, s4, 0x3000
	s_addc_u32 s5, s5, 0
	global_load_dword v107, v86, s[4:5]
	s_add_u32 s4, s4, 0x3000
	s_addc_u32 s5, s5, 0
	global_load_dword v108, v86, s[4:5]
	s_add_u32 s4, s4, 0x3000
	s_addc_u32 s5, s5, 0
	global_load_dword v109, v86, s[4:5]
	s_add_u32 s4, s4, 0x3000
	s_addc_u32 s5, s5, 0
	global_load_dword v110, v86, s[4:5]
	s_add_u32 s4, s4, 0x3000
	s_addc_u32 s5, s5, 0
	global_load_dword v111, v86, s[4:5]
	s_add_u32 s4, s4, 0x3000
	s_addc_u32 s5, s5, 0
	global_load_dword v112, v86, s[4:5]
	s_add_u32 s4, s4, 0x3000
	s_addc_u32 s5, s5, 0
	global_load_dword v113, v86, s[4:5]
	s_add_u32 s4, s4, 0x3000
	s_addc_u32 s5, s5, 0
	global_load_dword v114, v86, s[4:5]
	s_add_u32 s4, s4, 0x3000
	s_addc_u32 s5, s5, 0
	global_load_dword v115, v86, s[4:5]
	s_add_u32 s4, s4, 0x3000
	s_addc_u32 s5, s5, 0
	global_load_dword v116, v86, s[4:5]
	s_add_u32 s4, s4, 0x3000
	s_addc_u32 s5, s5, 0
	global_load_dword v117, v86, s[4:5]
	s_add_u32 s4, s4, 0x3000
	s_addc_u32 s5, s5, 0
	global_load_dword v118, v86, s[4:5]
	s_add_u32 s4, s4, 0x3000
	s_addc_u32 s5, s5, 0
	global_load_dword v119, v86, s[4:5]
	s_add_u32 s4, s4, 0x3000
	s_addc_u32 s5, s5, 0
	global_load_dword v120, v86, s[4:5]
	s_add_u32 s4, s4, 0x3000
	s_addc_u32 s5, s5, 0
	global_load_dword v121, v86, s[4:5]
	s_add_u32 s4, s4, 0x3000
	s_addc_u32 s5, s5, 0
	global_load_dword v122, v86, s[4:5]
	s_add_u32 s4, s4, 0x3000
	s_addc_u32 s5, s5, 0
	global_load_dword v123, v86, s[4:5]
	s_add_u32 s4, s4, 0x3000
	s_addc_u32 s5, s5, 0
	global_load_dword v124, v86, s[4:5]
	s_add_u32 s4, s4, 0x3000
	s_addc_u32 s5, s5, 0
	global_load_dword v125, v86, s[4:5]
	s_add_u32 s4, s4, 0x3000
	s_addc_u32 s5, s5, 0
	global_load_dword v126, v86, s[4:5]
	s_add_u32 s4, s4, 0x3000
	s_addc_u32 s5, s5, 0
	global_load_dword v127, v86, s[4:5]
	s_add_u32 s4, s4, 0x3000
	s_addc_u32 s5, s5, 0
	global_load_dword v128, v86, s[4:5]
	s_add_u32 s4, s4, 0x3000
	s_addc_u32 s5, s5, 0
	global_load_dword v129, v86, s[4:5]
	s_add_u32 s4, s4, 0x3000
	s_addc_u32 s5, s5, 0
	global_load_dword v130, v86, s[4:5]
	s_add_u32 s4, s4, 0x3000
	s_addc_u32 s5, s5, 0
	global_load_dword v131, v86, s[4:5]
	s_add_u32 s4, s4, 0x3000
	s_addc_u32 s5, s5, 0
	global_load_dword v132, v86, s[4:5]
	s_add_u32 s4, s4, 0x3000
	s_addc_u32 s5, s5, 0
	global_load_dword v133, v86, s[4:5]
	s_add_u32 s4, s4, 0x3000
	s_addc_u32 s5, s5, 0
	global_load_dword v134, v86, s[4:5]
	s_add_u32 s4, s4, 0x3000
	s_addc_u32 s5, s5, 0
	global_load_dword v135, v86, s[4:5]
	s_add_u32 s4, s4, 0x3000
	s_addc_u32 s5, s5, 0
	global_load_dword v136, v86, s[4:5]
	s_add_u32 s4, s4, 0x3000
	s_addc_u32 s5, s5, 0
	global_load_dword v137, v86, s[4:5]
	s_add_u32 s4, s4, 0x3000
	s_addc_u32 s5, s5, 0
	global_load_dword v138, v86, s[4:5]
	s_add_u32 s4, s4, 0x3000
	s_addc_u32 s5, s5, 0
	global_load_dword v139, v86, s[4:5]
	s_add_u32 s4, s4, 0x3000
	s_addc_u32 s5, s5, 0
	global_load_dword v140, v86, s[4:5]
	s_add_u32 s4, s4, 0x3000
	s_addc_u32 s5, s5, 0
	global_load_dword v141, v86, s[4:5]
	s_add_u32 s4, s4, 0x3000
	s_addc_u32 s5, s5, 0
	global_load_dword v142, v86, s[4:5]
	s_add_u32 s4, s4, 0x3000
	s_addc_u32 s5, s5, 0
	global_load_dword v143, v86, s[4:5]
	s_add_u32 s4, s4, 0x3000
	s_addc_u32 s5, s5, 0
	global_load_dword v144, v86, s[4:5]
	s_add_u32 s4, s4, 0x3000
	s_addc_u32 s5, s5, 0
	global_load_dword v145, v86, s[4:5]
	s_add_u32 s4, s4, 0x3000
	s_addc_u32 s5, s5, 0
	global_load_dword v146, v86, s[4:5]
	s_add_u32 s4, s4, 0x3000
	s_addc_u32 s5, s5, 0
	global_load_dword v147, v86, s[4:5]
	s_add_u32 s4, s4, 0x3000
	s_addc_u32 s5, s5, 0
	global_load_dword v148, v86, s[4:5]
	s_add_u32 s4, s4, 0x3000
	s_addc_u32 s5, s5, 0
	global_load_dword v149, v86, s[4:5]
	s_add_u32 s4, s4, 0x3000
	s_addc_u32 s5, s5, 0
	global_load_dword v150, v86, s[4:5]
	s_add_u32 s4, s4, 0x3000
	s_addc_u32 s5, s5, 0
	global_load_dword v151, v86, s[4:5]
	s_add_u32 s4, s4, 0x3000
	s_addc_u32 s5, s5, 0
	global_load_dword v152, v86, s[4:5]
	s_add_u32 s4, s4, 0x3000
	s_addc_u32 s5, s5, 0
	global_load_dword v153, v86, s[4:5]
	s_add_u32 s4, s4, 0x3000
	s_addc_u32 s5, s5, 0
	global_load_dword v154, v86, s[4:5]
	s_add_u32 s4, s4, 0x3000
	s_addc_u32 s5, s5, 0
	global_load_dword v155, v86, s[4:5]
	s_add_u32 s4, s4, 0x3000
	s_addc_u32 s5, s5, 0
	global_load_dword v156, v86, s[4:5]
	s_add_u32 s4, s4, 0x3000
	s_addc_u32 s5, s5, 0
	global_load_dword v157, v86, s[4:5]
	s_add_u32 s4, s4, 0x3000
	s_addc_u32 s5, s5, 0
	global_load_dword v158, v86, s[4:5]
	s_add_u32 s4, s4, 0x3000
	s_addc_u32 s5, s5, 0
	global_load_dword v159, v86, s[4:5]
	s_add_u32 s4, s4, 0x3000
	s_addc_u32 s5, s5, 0
	global_load_dword v164, v86, s[4:5]
	s_add_u32 s4, s4, 0x3000
	s_addc_u32 s5, s5, 0
	global_load_dword v165, v86, s[4:5]
	s_add_u32 s4, s4, 0x3000
	s_addc_u32 s5, s5, 0
	global_load_dword v166, v86, s[4:5]
	s_add_u32 s4, s4, 0x3000
	s_addc_u32 s5, s5, 0
	global_load_dword v167, v86, s[4:5]
	s_add_u32 s4, s4, 0x3000
	s_addc_u32 s5, s5, 0
	s_waitcnt vmcnt(56)
; DI void phase0(const Params& p, unsigned char* shm, int tid) {
;     ...
;       for (int k = 0; k < 128; ++k) {
;         const float w = wp[(size_t)k * 3072]; const int kk = kc * 128 + k;
;         a0 += ssc[kk] * w; a1 += ssc[1024 + kk] * w; a2 += ssc[2048 + kk] * w; a3 += ssc[3072 + kk] * w;
;       }
	v_mov_b32_e32 v74, v100
	v_mov_b32_e32 v70, v101
	v_mov_b32_e32 v72, v102
	v_mov_b32_e32 v76, v103
	v_mov_b32_e32 v68, v104
	v_mov_b32_e32 v78, v105
	v_mov_b32_e32 v80, v106
	v_mov_b32_e32 v82, v107
	v_add_u32_e32 v36, s28, v19
	v_add_u32_e32 v37, 0x11000, v36
	v_add_u32_e32 v40, 0x12000, v36
	v_add_u32_e32 v44, 0x13000, v36
	v_add_u32_e32 v48, 0x14000, v36
	v_add_u32_e32 v52, 0x11010, v36
	v_add_u32_e32 v56, 0x12010, v36
	v_add_u32_e32 v60, 0x13010, v36
	v_add_u32_e32 v64, 0x14010, v36
	ds_read_b128 v[36:39], v37
	ds_read_b128 v[40:43], v40
	ds_read_b128 v[44:47], v44
	ds_read_b128 v[48:51], v48
	ds_read_b128 v[52:55], v52
	ds_read_b128 v[56:59], v56
	ds_read_b128 v[60:63], v60
	ds_read_b128 v[64:67], v64
	s_waitcnt lgkmcnt(7)
	v_mov_b32_e32 v84, v36
	s_waitcnt lgkmcnt(6)
	v_mov_b32_e32 v85, v40
	v_mov_b32_e32 v40, v37
	v_mov_b32_e32 v36, v38
	v_mov_b32_e32 v37, v42
	v_mov_b32_e32 v42, v39
	s_waitcnt lgkmcnt(5)
	v_mov_b32_e32 v38, v44
	s_waitcnt lgkmcnt(4)
	v_mov_b32_e32 v39, v48
	v_mov_b32_e32 v48, v45
	v_mov_b32_e32 v44, v46
	v_mov_b32_e32 v45, v50
	v_mov_b32_e32 v50, v47
	s_waitcnt lgkmcnt(3)
	v_mov_b32_e32 v46, v52
	s_waitcnt lgkmcnt(2)
	v_mov_b32_e32 v47, v56
	v_mov_b32_e32 v56, v53
	v_mov_b32_e32 v52, v54
	v_mov_b32_e32 v53, v58
	v_mov_b32_e32 v58, v55
	s_waitcnt lgkmcnt(1)
	v_mov_b32_e32 v54, v60
	s_waitcnt lgkmcnt(0)
	v_mov_b32_e32 v55, v64
	v_mov_b32_e32 v64, v61
	v_mov_b32_e32 v60, v62
	v_mov_b32_e32 v61, v66
	s_add_i32 s28, s28, 32
	v_mov_b32_e32 v66, v63
	v_pk_fma_f32 v[12:13], v[74:75], v[84:85], v[12:13] op_sel_hi:[0,1,1]
	v_pk_fma_f32 v[14:15], v[74:75], v[38:39], v[14:15] op_sel_hi:[0,1,1]
	v_pk_fma_f32 v[12:13], v[70:71], v[40:41], v[12:13] op_sel_hi:[0,1,1]
	v_pk_fma_f32 v[14:15], v[70:71], v[48:49], v[14:15] op_sel_hi:[0,1,1]
	v_pk_fma_f32 v[12:13], v[72:73], v[36:37], v[12:13] op_sel_hi:[0,1,1]
	v_pk_fma_f32 v[14:15], v[72:73], v[44:45], v[14:15] op_sel_hi:[0,1,1]
	v_pk_fma_f32 v[12:13], v[76:77], v[42:43], v[12:13] op_sel_hi:[0,1,1]
	v_pk_fma_f32 v[14:15], v[76:77], v[50:51], v[14:15] op_sel_hi:[0,1,1]
	v_pk_fma_f32 v[12:13], v[68:69], v[46:47], v[12:13] op_sel_hi:[0,1,1]
	v_pk_fma_f32 v[14:15], v[68:69], v[54:55], v[14:15] op_sel_hi:[0,1,1]
	v_pk_fma_f32 v[12:13], v[78:79], v[56:57], v[12:13] op_sel_hi:[0,1,1]
	v_pk_fma_f32 v[14:15], v[78:79], v[64:65], v[14:15] op_sel_hi:[0,1,1]
	v_pk_fma_f32 v[12:13], v[80:81], v[52:53], v[12:13] op_sel_hi:[0,1,1]
	v_pk_fma_f32 v[14:15], v[80:81], v[60:61], v[14:15] op_sel_hi:[0,1,1]
	v_pk_fma_f32 v[12:13], v[82:83], v[58:59], v[12:13] op_sel_hi:[0,1,1]
	v_pk_fma_f32 v[14:15], v[82:83], v[66:67], v[14:15] op_sel_hi:[0,1,1]
	global_load_dword v168, v86, s[4:5]
	s_add_u32 s4, s4, 0x3000
	s_addc_u32 s5, s5, 0
	global_load_dword v169, v86, s[4:5]
	s_add_u32 s4, s4, 0x3000
	s_addc_u32 s5, s5, 0
	global_load_dword v170, v86, s[4:5]
	s_add_u32 s4, s4, 0x3000
	s_addc_u32 s5, s5, 0
	global_load_dword v171, v86, s[4:5]
	s_add_u32 s4, s4, 0x3000
	s_addc_u32 s5, s5, 0
	global_load_dword v172, v86, s[4:5]
	s_add_u32 s4, s4, 0x3000
	s_addc_u32 s5, s5, 0
	global_load_dword v173, v86, s[4:5]
	s_add_u32 s4, s4, 0x3000
	s_addc_u32 s5, s5, 0
	global_load_dword v174, v86, s[4:5]
	s_add_u32 s4, s4, 0x3000
	s_addc_u32 s5, s5, 0
	global_load_dword v175, v86, s[4:5]
	s_add_u32 s4, s4, 0x3000
	s_addc_u32 s5, s5, 0
	s_waitcnt vmcnt(56)
	v_mov_b32_e32 v74, v108
	v_mov_b32_e32 v70, v109
	v_mov_b32_e32 v72, v110
	v_mov_b32_e32 v76, v111
	v_mov_b32_e32 v68, v112
	v_mov_b32_e32 v78, v113
	v_mov_b32_e32 v80, v114
	v_mov_b32_e32 v82, v115
	v_add_u32_e32 v36, s28, v19
	v_add_u32_e32 v37, 0x11000, v36
	v_add_u32_e32 v40, 0x12000, v36
	v_add_u32_e32 v44, 0x13000, v36
	v_add_u32_e32 v48, 0x14000, v36
	v_add_u32_e32 v52, 0x11010, v36
	v_add_u32_e32 v56, 0x12010, v36
	v_add_u32_e32 v60, 0x13010, v36
	v_add_u32_e32 v64, 0x14010, v36
	ds_read_b128 v[36:39], v37
	ds_read_b128 v[40:43], v40
	ds_read_b128 v[44:47], v44
	ds_read_b128 v[48:51], v48
	ds_read_b128 v[52:55], v52
	ds_read_b128 v[56:59], v56
	ds_read_b128 v[60:63], v60
	ds_read_b128 v[64:67], v64
	s_waitcnt lgkmcnt(7)
	v_mov_b32_e32 v84, v36
	s_waitcnt lgkmcnt(6)
	v_mov_b32_e32 v85, v40
	v_mov_b32_e32 v40, v37
	v_mov_b32_e32 v36, v38
	v_mov_b32_e32 v37, v42
	v_mov_b32_e32 v42, v39
	s_waitcnt lgkmcnt(5)
	v_mov_b32_e32 v38, v44
	s_waitcnt lgkmcnt(4)
	v_mov_b32_e32 v39, v48
	v_mov_b32_e32 v48, v45
	v_mov_b32_e32 v44, v46
	v_mov_b32_e32 v45, v50
	v_mov_b32_e32 v50, v47
	s_waitcnt lgkmcnt(3)
	v_mov_b32_e32 v46, v52
	s_waitcnt lgkmcnt(2)
	v_mov_b32_e32 v47, v56
	v_mov_b32_e32 v56, v53
	v_mov_b32_e32 v52, v54
	v_mov_b32_e32 v53, v58
	v_mov_b32_e32 v58, v55
	s_waitcnt lgkmcnt(1)
	v_mov_b32_e32 v54, v60
	s_waitcnt lgkmcnt(0)
; DI void phase0(const Params& p, unsigned char* shm, int tid) {
;     ...
;       for (int k = 0; k < 128; ++k) {
;         const float w = wp[(size_t)k * 3072]; const int kk = kc * 128 + k;
;         a0 += ssc[kk] * w; a1 += ssc[1024 + kk] * w; a2 += ssc[2048 + kk] * w; a3 += ssc[3072 + kk] * w;
;       }
	v_mov_b32_e32 v55, v64
	v_mov_b32_e32 v64, v61
	v_mov_b32_e32 v60, v62
	v_mov_b32_e32 v61, v66
	s_add_i32 s28, s28, 32
	v_mov_b32_e32 v66, v63
	v_pk_fma_f32 v[12:13], v[74:75], v[84:85], v[12:13] op_sel_hi:[0,1,1]
	v_pk_fma_f32 v[14:15], v[74:75], v[38:39], v[14:15] op_sel_hi:[0,1,1]
	v_pk_fma_f32 v[12:13], v[70:71], v[40:41], v[12:13] op_sel_hi:[0,1,1]
	v_pk_fma_f32 v[14:15], v[70:71], v[48:49], v[14:15] op_sel_hi:[0,1,1]
	v_pk_fma_f32 v[12:13], v[72:73], v[36:37], v[12:13] op_sel_hi:[0,1,1]
	v_pk_fma_f32 v[14:15], v[72:73], v[44:45], v[14:15] op_sel_hi:[0,1,1]
	v_pk_fma_f32 v[12:13], v[76:77], v[42:43], v[12:13] op_sel_hi:[0,1,1]
	v_pk_fma_f32 v[14:15], v[76:77], v[50:51], v[14:15] op_sel_hi:[0,1,1]
	v_pk_fma_f32 v[12:13], v[68:69], v[46:47], v[12:13] op_sel_hi:[0,1,1]
	v_pk_fma_f32 v[14:15], v[68:69], v[54:55], v[14:15] op_sel_hi:[0,1,1]
	v_pk_fma_f32 v[12:13], v[78:79], v[56:57], v[12:13] op_sel_hi:[0,1,1]
	v_pk_fma_f32 v[14:15], v[78:79], v[64:65], v[14:15] op_sel_hi:[0,1,1]
	v_pk_fma_f32 v[12:13], v[80:81], v[52:53], v[12:13] op_sel_hi:[0,1,1]
	v_pk_fma_f32 v[14:15], v[80:81], v[60:61], v[14:15] op_sel_hi:[0,1,1]
	v_pk_fma_f32 v[12:13], v[82:83], v[58:59], v[12:13] op_sel_hi:[0,1,1]
	v_pk_fma_f32 v[14:15], v[82:83], v[66:67], v[14:15] op_sel_hi:[0,1,1]
	global_load_dword v176, v86, s[4:5]
	s_add_u32 s4, s4, 0x3000
	s_addc_u32 s5, s5, 0
	global_load_dword v177, v86, s[4:5]
	s_add_u32 s4, s4, 0x3000
	s_addc_u32 s5, s5, 0
	global_load_dword v178, v86, s[4:5]
	s_add_u32 s4, s4, 0x3000
	s_addc_u32 s5, s5, 0
	global_load_dword v179, v86, s[4:5]
	s_add_u32 s4, s4, 0x3000
	s_addc_u32 s5, s5, 0
	global_load_dword v180, v86, s[4:5]
	s_add_u32 s4, s4, 0x3000
	s_addc_u32 s5, s5, 0
	global_load_dword v181, v86, s[4:5]
	s_add_u32 s4, s4, 0x3000
	s_addc_u32 s5, s5, 0
	global_load_dword v182, v86, s[4:5]
	s_add_u32 s4, s4, 0x3000
	s_addc_u32 s5, s5, 0
	global_load_dword v183, v86, s[4:5]
	s_add_u32 s4, s4, 0x3000
	s_addc_u32 s5, s5, 0
	s_waitcnt vmcnt(56)
	v_mov_b32_e32 v74, v116
	v_mov_b32_e32 v70, v117
	v_mov_b32_e32 v72, v118
	v_mov_b32_e32 v76, v119
	v_mov_b32_e32 v68, v120
	v_mov_b32_e32 v78, v121
	v_mov_b32_e32 v80, v122
	v_mov_b32_e32 v82, v123
	v_add_u32_e32 v36, s28, v19
	v_add_u32_e32 v37, 0x11000, v36
	v_add_u32_e32 v40, 0x12000, v36
	v_add_u32_e32 v44, 0x13000, v36
	v_add_u32_e32 v48, 0x14000, v36
	v_add_u32_e32 v52, 0x11010, v36
	v_add_u32_e32 v56, 0x12010, v36
	v_add_u32_e32 v60, 0x13010, v36
	v_add_u32_e32 v64, 0x14010, v36
	ds_read_b128 v[36:39], v37
	ds_read_b128 v[40:43], v40
	ds_read_b128 v[44:47], v44
	ds_read_b128 v[48:51], v48
	ds_read_b128 v[52:55], v52
	ds_read_b128 v[56:59], v56
	ds_read_b128 v[60:63], v60
	ds_read_b128 v[64:67], v64
	s_waitcnt lgkmcnt(7)
	v_mov_b32_e32 v84, v36
	s_waitcnt lgkmcnt(6)
	v_mov_b32_e32 v85, v40
	v_mov_b32_e32 v40, v37
	v_mov_b32_e32 v36, v38
	v_mov_b32_e32 v37, v42
	v_mov_b32_e32 v42, v39
	s_waitcnt lgkmcnt(5)
	v_mov_b32_e32 v38, v44
	s_waitcnt lgkmcnt(4)
	v_mov_b32_e32 v39, v48
	v_mov_b32_e32 v48, v45
	v_mov_b32_e32 v44, v46
	v_mov_b32_e32 v45, v50
	v_mov_b32_e32 v50, v47
	s_waitcnt lgkmcnt(3)
	v_mov_b32_e32 v46, v52
	s_waitcnt lgkmcnt(2)
	v_mov_b32_e32 v47, v56
	v_mov_b32_e32 v56, v53
	v_mov_b32_e32 v52, v54
	v_mov_b32_e32 v53, v58
	v_mov_b32_e32 v58, v55
	s_waitcnt lgkmcnt(1)
	v_mov_b32_e32 v54, v60
	s_waitcnt lgkmcnt(0)
	v_mov_b32_e32 v55, v64
	v_mov_b32_e32 v64, v61
	v_mov_b32_e32 v60, v62
	v_mov_b32_e32 v61, v66
	s_add_i32 s28, s28, 32
	v_mov_b32_e32 v66, v63
	v_pk_fma_f32 v[12:13], v[74:75], v[84:85], v[12:13] op_sel_hi:[0,1,1]
	v_pk_fma_f32 v[14:15], v[74:75], v[38:39], v[14:15] op_sel_hi:[0,1,1]
	v_pk_fma_f32 v[12:13], v[70:71], v[40:41], v[12:13] op_sel_hi:[0,1,1]
	v_pk_fma_f32 v[14:15], v[70:71], v[48:49], v[14:15] op_sel_hi:[0,1,1]
	v_pk_fma_f32 v[12:13], v[72:73], v[36:37], v[12:13] op_sel_hi:[0,1,1]
	v_pk_fma_f32 v[14:15], v[72:73], v[44:45], v[14:15] op_sel_hi:[0,1,1]
	v_pk_fma_f32 v[12:13], v[76:77], v[42:43], v[12:13] op_sel_hi:[0,1,1]
	v_pk_fma_f32 v[14:15], v[76:77], v[50:51], v[14:15] op_sel_hi:[0,1,1]
	v_pk_fma_f32 v[12:13], v[68:69], v[46:47], v[12:13] op_sel_hi:[0,1,1]
	v_pk_fma_f32 v[14:15], v[68:69], v[54:55], v[14:15] op_sel_hi:[0,1,1]
	v_pk_fma_f32 v[12:13], v[78:79], v[56:57], v[12:13] op_sel_hi:[0,1,1]
	v_pk_fma_f32 v[14:15], v[78:79], v[64:65], v[14:15] op_sel_hi:[0,1,1]
	v_pk_fma_f32 v[12:13], v[80:81], v[52:53], v[12:13] op_sel_hi:[0,1,1]
	v_pk_fma_f32 v[14:15], v[80:81], v[60:61], v[14:15] op_sel_hi:[0,1,1]
	v_pk_fma_f32 v[12:13], v[82:83], v[58:59], v[12:13] op_sel_hi:[0,1,1]
	v_pk_fma_f32 v[14:15], v[82:83], v[66:67], v[14:15] op_sel_hi:[0,1,1]
	global_load_dword v184, v86, s[4:5]
	s_add_u32 s4, s4, 0x3000
	s_addc_u32 s5, s5, 0
	global_load_dword v185, v86, s[4:5]
	s_add_u32 s4, s4, 0x3000
	s_addc_u32 s5, s5, 0
	global_load_dword v186, v86, s[4:5]
	s_add_u32 s4, s4, 0x3000
	s_addc_u32 s5, s5, 0
	global_load_dword v187, v86, s[4:5]
	s_add_u32 s4, s4, 0x3000
	s_addc_u32 s5, s5, 0
	global_load_dword v188, v86, s[4:5]
	s_add_u32 s4, s4, 0x3000
	s_addc_u32 s5, s5, 0
	global_load_dword v189, v86, s[4:5]
	s_add_u32 s4, s4, 0x3000
	s_addc_u32 s5, s5, 0
	global_load_dword v190, v86, s[4:5]
	s_add_u32 s4, s4, 0x3000
	s_addc_u32 s5, s5, 0
	global_load_dword v191, v86, s[4:5]
	s_add_u32 s4, s4, 0x3000
	s_addc_u32 s5, s5, 0
	s_waitcnt vmcnt(56)
; DI void phase0(const Params& p, unsigned char* shm, int tid) {
;     ...
;       for (int k = 0; k < 128; ++k) {
;         const float w = wp[(size_t)k * 3072]; const int kk = kc * 128 + k;
;         a0 += ssc[kk] * w; a1 += ssc[1024 + kk] * w; a2 += ssc[2048 + kk] * w; a3 += ssc[3072 + kk] * w;
;       }
	v_mov_b32_e32 v74, v124
	v_mov_b32_e32 v70, v125
	v_mov_b32_e32 v72, v126
	v_mov_b32_e32 v76, v127
	v_mov_b32_e32 v68, v128
	v_mov_b32_e32 v78, v129
	v_mov_b32_e32 v80, v130
	v_mov_b32_e32 v82, v131
	v_add_u32_e32 v36, s28, v19
	v_add_u32_e32 v37, 0x11000, v36
	v_add_u32_e32 v40, 0x12000, v36
	v_add_u32_e32 v44, 0x13000, v36
	v_add_u32_e32 v48, 0x14000, v36
	v_add_u32_e32 v52, 0x11010, v36
	v_add_u32_e32 v56, 0x12010, v36
	v_add_u32_e32 v60, 0x13010, v36
	v_add_u32_e32 v64, 0x14010, v36
	ds_read_b128 v[36:39], v37
	ds_read_b128 v[40:43], v40
	ds_read_b128 v[44:47], v44
	ds_read_b128 v[48:51], v48
	ds_read_b128 v[52:55], v52
	ds_read_b128 v[56:59], v56
	ds_read_b128 v[60:63], v60
	ds_read_b128 v[64:67], v64
	s_waitcnt lgkmcnt(7)
	v_mov_b32_e32 v84, v36
	s_waitcnt lgkmcnt(6)
	v_mov_b32_e32 v85, v40
	v_mov_b32_e32 v40, v37
	v_mov_b32_e32 v36, v38
	v_mov_b32_e32 v37, v42
	v_mov_b32_e32 v42, v39
	s_waitcnt lgkmcnt(5)
	v_mov_b32_e32 v38, v44
	s_waitcnt lgkmcnt(4)
	v_mov_b32_e32 v39, v48
	v_mov_b32_e32 v48, v45
	v_mov_b32_e32 v44, v46
	v_mov_b32_e32 v45, v50
	v_mov_b32_e32 v50, v47
	s_waitcnt lgkmcnt(3)
	v_mov_b32_e32 v46, v52
	s_waitcnt lgkmcnt(2)
	v_mov_b32_e32 v47, v56
	v_mov_b32_e32 v56, v53
	v_mov_b32_e32 v52, v54
	v_mov_b32_e32 v53, v58
	v_mov_b32_e32 v58, v55
	s_waitcnt lgkmcnt(1)
	v_mov_b32_e32 v54, v60
	s_waitcnt lgkmcnt(0)
	v_mov_b32_e32 v55, v64
	v_mov_b32_e32 v64, v61
	v_mov_b32_e32 v60, v62
	v_mov_b32_e32 v61, v66
	s_add_i32 s28, s28, 32
	v_mov_b32_e32 v66, v63
	v_pk_fma_f32 v[12:13], v[74:75], v[84:85], v[12:13] op_sel_hi:[0,1,1]
	v_pk_fma_f32 v[14:15], v[74:75], v[38:39], v[14:15] op_sel_hi:[0,1,1]
	v_pk_fma_f32 v[12:13], v[70:71], v[40:41], v[12:13] op_sel_hi:[0,1,1]
	v_pk_fma_f32 v[14:15], v[70:71], v[48:49], v[14:15] op_sel_hi:[0,1,1]
	v_pk_fma_f32 v[12:13], v[72:73], v[36:37], v[12:13] op_sel_hi:[0,1,1]
	v_pk_fma_f32 v[14:15], v[72:73], v[44:45], v[14:15] op_sel_hi:[0,1,1]
	v_pk_fma_f32 v[12:13], v[76:77], v[42:43], v[12:13] op_sel_hi:[0,1,1]
	v_pk_fma_f32 v[14:15], v[76:77], v[50:51], v[14:15] op_sel_hi:[0,1,1]
	v_pk_fma_f32 v[12:13], v[68:69], v[46:47], v[12:13] op_sel_hi:[0,1,1]
	v_pk_fma_f32 v[14:15], v[68:69], v[54:55], v[14:15] op_sel_hi:[0,1,1]
	v_pk_fma_f32 v[12:13], v[78:79], v[56:57], v[12:13] op_sel_hi:[0,1,1]
	v_pk_fma_f32 v[14:15], v[78:79], v[64:65], v[14:15] op_sel_hi:[0,1,1]
	v_pk_fma_f32 v[12:13], v[80:81], v[52:53], v[12:13] op_sel_hi:[0,1,1]
	v_pk_fma_f32 v[14:15], v[80:81], v[60:61], v[14:15] op_sel_hi:[0,1,1]
	v_pk_fma_f32 v[12:13], v[82:83], v[58:59], v[12:13] op_sel_hi:[0,1,1]
	v_pk_fma_f32 v[14:15], v[82:83], v[66:67], v[14:15] op_sel_hi:[0,1,1]
	global_load_dword v192, v86, s[4:5]
	s_add_u32 s4, s4, 0x3000
	s_addc_u32 s5, s5, 0
	global_load_dword v193, v86, s[4:5]
	s_add_u32 s4, s4, 0x3000
	s_addc_u32 s5, s5, 0
	global_load_dword v194, v86, s[4:5]
	s_add_u32 s4, s4, 0x3000
	s_addc_u32 s5, s5, 0
	global_load_dword v195, v86, s[4:5]
	s_add_u32 s4, s4, 0x3000
	s_addc_u32 s5, s5, 0
	global_load_dword v196, v86, s[4:5]
	s_add_u32 s4, s4, 0x3000
	s_addc_u32 s5, s5, 0
	global_load_dword v197, v86, s[4:5]
	s_add_u32 s4, s4, 0x3000
	s_addc_u32 s5, s5, 0
	global_load_dword v198, v86, s[4:5]
	s_add_u32 s4, s4, 0x3000
	s_addc_u32 s5, s5, 0
	global_load_dword v199, v86, s[4:5]
	s_add_u32 s4, s4, 0x3000
	s_addc_u32 s5, s5, 0
	s_waitcnt vmcnt(56)
	v_mov_b32_e32 v74, v132
	v_mov_b32_e32 v70, v133
	v_mov_b32_e32 v72, v134
	v_mov_b32_e32 v76, v135
	v_mov_b32_e32 v68, v136
	v_mov_b32_e32 v78, v137
	v_mov_b32_e32 v80, v138
	v_mov_b32_e32 v82, v139
	v_add_u32_e32 v36, s28, v19
	v_add_u32_e32 v37, 0x11000, v36
	v_add_u32_e32 v40, 0x12000, v36
	v_add_u32_e32 v44, 0x13000, v36
	v_add_u32_e32 v48, 0x14000, v36
	v_add_u32_e32 v52, 0x11010, v36
	v_add_u32_e32 v56, 0x12010, v36
	v_add_u32_e32 v60, 0x13010, v36
	v_add_u32_e32 v64, 0x14010, v36
	ds_read_b128 v[36:39], v37
	ds_read_b128 v[40:43], v40
	ds_read_b128 v[44:47], v44
	ds_read_b128 v[48:51], v48
	ds_read_b128 v[52:55], v52
	ds_read_b128 v[56:59], v56
	ds_read_b128 v[60:63], v60
	ds_read_b128 v[64:67], v64
	s_waitcnt lgkmcnt(7)
	v_mov_b32_e32 v84, v36
	s_waitcnt lgkmcnt(6)
	v_mov_b32_e32 v85, v40
	v_mov_b32_e32 v40, v37
	v_mov_b32_e32 v36, v38
	v_mov_b32_e32 v37, v42
	v_mov_b32_e32 v42, v39
	s_waitcnt lgkmcnt(5)
	v_mov_b32_e32 v38, v44
	s_waitcnt lgkmcnt(4)
	v_mov_b32_e32 v39, v48
	v_mov_b32_e32 v48, v45
	v_mov_b32_e32 v44, v46
	v_mov_b32_e32 v45, v50
	v_mov_b32_e32 v50, v47
	s_waitcnt lgkmcnt(3)
	v_mov_b32_e32 v46, v52
	s_waitcnt lgkmcnt(2)
	v_mov_b32_e32 v47, v56
	v_mov_b32_e32 v56, v53
	v_mov_b32_e32 v52, v54
	v_mov_b32_e32 v53, v58
	v_mov_b32_e32 v58, v55
	s_waitcnt lgkmcnt(1)
	v_mov_b32_e32 v54, v60
	s_waitcnt lgkmcnt(0)
; DI void phase0(const Params& p, unsigned char* shm, int tid) {
;     ...
;       for (int k = 0; k < 128; ++k) {
;         const float w = wp[(size_t)k * 3072]; const int kk = kc * 128 + k;
;         a0 += ssc[kk] * w; a1 += ssc[1024 + kk] * w; a2 += ssc[2048 + kk] * w; a3 += ssc[3072 + kk] * w;
;       }
	v_mov_b32_e32 v55, v64
	v_mov_b32_e32 v64, v61
	v_mov_b32_e32 v60, v62
	v_mov_b32_e32 v61, v66
	s_add_i32 s28, s28, 32
	v_mov_b32_e32 v66, v63
	v_pk_fma_f32 v[12:13], v[74:75], v[84:85], v[12:13] op_sel_hi:[0,1,1]
	v_pk_fma_f32 v[14:15], v[74:75], v[38:39], v[14:15] op_sel_hi:[0,1,1]
	v_pk_fma_f32 v[12:13], v[70:71], v[40:41], v[12:13] op_sel_hi:[0,1,1]
	v_pk_fma_f32 v[14:15], v[70:71], v[48:49], v[14:15] op_sel_hi:[0,1,1]
	v_pk_fma_f32 v[12:13], v[72:73], v[36:37], v[12:13] op_sel_hi:[0,1,1]
	v_pk_fma_f32 v[14:15], v[72:73], v[44:45], v[14:15] op_sel_hi:[0,1,1]
	v_pk_fma_f32 v[12:13], v[76:77], v[42:43], v[12:13] op_sel_hi:[0,1,1]
	v_pk_fma_f32 v[14:15], v[76:77], v[50:51], v[14:15] op_sel_hi:[0,1,1]
	v_pk_fma_f32 v[12:13], v[68:69], v[46:47], v[12:13] op_sel_hi:[0,1,1]
	v_pk_fma_f32 v[14:15], v[68:69], v[54:55], v[14:15] op_sel_hi:[0,1,1]
	v_pk_fma_f32 v[12:13], v[78:79], v[56:57], v[12:13] op_sel_hi:[0,1,1]
	v_pk_fma_f32 v[14:15], v[78:79], v[64:65], v[14:15] op_sel_hi:[0,1,1]
	v_pk_fma_f32 v[12:13], v[80:81], v[52:53], v[12:13] op_sel_hi:[0,1,1]
	v_pk_fma_f32 v[14:15], v[80:81], v[60:61], v[14:15] op_sel_hi:[0,1,1]
	v_pk_fma_f32 v[12:13], v[82:83], v[58:59], v[12:13] op_sel_hi:[0,1,1]
	v_pk_fma_f32 v[14:15], v[82:83], v[66:67], v[14:15] op_sel_hi:[0,1,1]
	global_load_dword v200, v86, s[4:5]
	s_add_u32 s4, s4, 0x3000
	s_addc_u32 s5, s5, 0
	global_load_dword v201, v86, s[4:5]
	s_add_u32 s4, s4, 0x3000
	s_addc_u32 s5, s5, 0
	global_load_dword v202, v86, s[4:5]
	s_add_u32 s4, s4, 0x3000
	s_addc_u32 s5, s5, 0
	global_load_dword v203, v86, s[4:5]
	s_add_u32 s4, s4, 0x3000
	s_addc_u32 s5, s5, 0
	global_load_dword v204, v86, s[4:5]
	s_add_u32 s4, s4, 0x3000
	s_addc_u32 s5, s5, 0
	global_load_dword v205, v86, s[4:5]
	s_add_u32 s4, s4, 0x3000
	s_addc_u32 s5, s5, 0
	global_load_dword v206, v86, s[4:5]
	s_add_u32 s4, s4, 0x3000
	s_addc_u32 s5, s5, 0
	global_load_dword v207, v86, s[4:5]
	s_add_u32 s4, s4, 0x3000
	s_addc_u32 s5, s5, 0
	s_waitcnt vmcnt(56)
	v_mov_b32_e32 v74, v140
	v_mov_b32_e32 v70, v141
	v_mov_b32_e32 v72, v142
	v_mov_b32_e32 v76, v143
	v_mov_b32_e32 v68, v144
	v_mov_b32_e32 v78, v145
	v_mov_b32_e32 v80, v146
	v_mov_b32_e32 v82, v147
	v_add_u32_e32 v36, s28, v19
	v_add_u32_e32 v37, 0x11000, v36
	v_add_u32_e32 v40, 0x12000, v36
	v_add_u32_e32 v44, 0x13000, v36
	v_add_u32_e32 v48, 0x14000, v36
	v_add_u32_e32 v52, 0x11010, v36
	v_add_u32_e32 v56, 0x12010, v36
	v_add_u32_e32 v60, 0x13010, v36
	v_add_u32_e32 v64, 0x14010, v36
	ds_read_b128 v[36:39], v37
	ds_read_b128 v[40:43], v40
	ds_read_b128 v[44:47], v44
	ds_read_b128 v[48:51], v48
	ds_read_b128 v[52:55], v52
	ds_read_b128 v[56:59], v56
	ds_read_b128 v[60:63], v60
	ds_read_b128 v[64:67], v64
	s_waitcnt lgkmcnt(7)
	v_mov_b32_e32 v84, v36
	s_waitcnt lgkmcnt(6)
	v_mov_b32_e32 v85, v40
	v_mov_b32_e32 v40, v37
	v_mov_b32_e32 v36, v38
	v_mov_b32_e32 v37, v42
	v_mov_b32_e32 v42, v39
	s_waitcnt lgkmcnt(5)
	v_mov_b32_e32 v38, v44
	s_waitcnt lgkmcnt(4)
	v_mov_b32_e32 v39, v48
	v_mov_b32_e32 v48, v45
	v_mov_b32_e32 v44, v46
	v_mov_b32_e32 v45, v50
	v_mov_b32_e32 v50, v47
	s_waitcnt lgkmcnt(3)
	v_mov_b32_e32 v46, v52
	s_waitcnt lgkmcnt(2)
	v_mov_b32_e32 v47, v56
	v_mov_b32_e32 v56, v53
	v_mov_b32_e32 v52, v54
	v_mov_b32_e32 v53, v58
	v_mov_b32_e32 v58, v55
	s_waitcnt lgkmcnt(1)
	v_mov_b32_e32 v54, v60
	s_waitcnt lgkmcnt(0)
	v_mov_b32_e32 v55, v64
	v_mov_b32_e32 v64, v61
	v_mov_b32_e32 v60, v62
	v_mov_b32_e32 v61, v66
	s_add_i32 s28, s28, 32
	v_mov_b32_e32 v66, v63
	v_pk_fma_f32 v[12:13], v[74:75], v[84:85], v[12:13] op_sel_hi:[0,1,1]
	v_pk_fma_f32 v[14:15], v[74:75], v[38:39], v[14:15] op_sel_hi:[0,1,1]
	v_pk_fma_f32 v[12:13], v[70:71], v[40:41], v[12:13] op_sel_hi:[0,1,1]
	v_pk_fma_f32 v[14:15], v[70:71], v[48:49], v[14:15] op_sel_hi:[0,1,1]
	v_pk_fma_f32 v[12:13], v[72:73], v[36:37], v[12:13] op_sel_hi:[0,1,1]
	v_pk_fma_f32 v[14:15], v[72:73], v[44:45], v[14:15] op_sel_hi:[0,1,1]
	v_pk_fma_f32 v[12:13], v[76:77], v[42:43], v[12:13] op_sel_hi:[0,1,1]
	v_pk_fma_f32 v[14:15], v[76:77], v[50:51], v[14:15] op_sel_hi:[0,1,1]
	v_pk_fma_f32 v[12:13], v[68:69], v[46:47], v[12:13] op_sel_hi:[0,1,1]
	v_pk_fma_f32 v[14:15], v[68:69], v[54:55], v[14:15] op_sel_hi:[0,1,1]
	v_pk_fma_f32 v[12:13], v[78:79], v[56:57], v[12:13] op_sel_hi:[0,1,1]
	v_pk_fma_f32 v[14:15], v[78:79], v[64:65], v[14:15] op_sel_hi:[0,1,1]
	v_pk_fma_f32 v[12:13], v[80:81], v[52:53], v[12:13] op_sel_hi:[0,1,1]
	v_pk_fma_f32 v[14:15], v[80:81], v[60:61], v[14:15] op_sel_hi:[0,1,1]
	v_pk_fma_f32 v[12:13], v[82:83], v[58:59], v[12:13] op_sel_hi:[0,1,1]
	v_pk_fma_f32 v[14:15], v[82:83], v[66:67], v[14:15] op_sel_hi:[0,1,1]
	global_load_dword v208, v86, s[4:5]
	s_add_u32 s4, s4, 0x3000
	s_addc_u32 s5, s5, 0
	global_load_dword v209, v86, s[4:5]
	s_add_u32 s4, s4, 0x3000
	s_addc_u32 s5, s5, 0
	global_load_dword v210, v86, s[4:5]
	s_add_u32 s4, s4, 0x3000
	s_addc_u32 s5, s5, 0
	global_load_dword v211, v86, s[4:5]
	s_add_u32 s4, s4, 0x3000
	s_addc_u32 s5, s5, 0
	global_load_dword v212, v86, s[4:5]
	s_add_u32 s4, s4, 0x3000
	s_addc_u32 s5, s5, 0
	global_load_dword v213, v86, s[4:5]
	s_add_u32 s4, s4, 0x3000
	s_addc_u32 s5, s5, 0
	global_load_dword v214, v86, s[4:5]
	s_add_u32 s4, s4, 0x3000
	s_addc_u32 s5, s5, 0
	global_load_dword v215, v86, s[4:5]
	s_add_u32 s4, s4, 0x3000
	s_addc_u32 s5, s5, 0
	s_waitcnt vmcnt(56)
; DI void phase0(const Params& p, unsigned char* shm, int tid) {
;     ...
;       for (int k = 0; k < 128; ++k) {
;         const float w = wp[(size_t)k * 3072]; const int kk = kc * 128 + k;
;         a0 += ssc[kk] * w; a1 += ssc[1024 + kk] * w; a2 += ssc[2048 + kk] * w; a3 += ssc[3072 + kk] * w;
;       }
	v_mov_b32_e32 v74, v148
	v_mov_b32_e32 v70, v149
	v_mov_b32_e32 v72, v150
	v_mov_b32_e32 v76, v151
	v_mov_b32_e32 v68, v152
	v_mov_b32_e32 v78, v153
	v_mov_b32_e32 v80, v154
	v_mov_b32_e32 v82, v155
	v_add_u32_e32 v36, s28, v19
	v_add_u32_e32 v37, 0x11000, v36
	v_add_u32_e32 v40, 0x12000, v36
	v_add_u32_e32 v44, 0x13000, v36
	v_add_u32_e32 v48, 0x14000, v36
	v_add_u32_e32 v52, 0x11010, v36
	v_add_u32_e32 v56, 0x12010, v36
	v_add_u32_e32 v60, 0x13010, v36
	v_add_u32_e32 v64, 0x14010, v36
	ds_read_b128 v[36:39], v37
	ds_read_b128 v[40:43], v40
	ds_read_b128 v[44:47], v44
	ds_read_b128 v[48:51], v48
	ds_read_b128 v[52:55], v52
	ds_read_b128 v[56:59], v56
	ds_read_b128 v[60:63], v60
	ds_read_b128 v[64:67], v64
	s_waitcnt lgkmcnt(7)
	v_mov_b32_e32 v84, v36
	s_waitcnt lgkmcnt(6)
	v_mov_b32_e32 v85, v40
	v_mov_b32_e32 v40, v37
	v_mov_b32_e32 v36, v38
	v_mov_b32_e32 v37, v42
	v_mov_b32_e32 v42, v39
	s_waitcnt lgkmcnt(5)
	v_mov_b32_e32 v38, v44
	s_waitcnt lgkmcnt(4)
	v_mov_b32_e32 v39, v48
	v_mov_b32_e32 v48, v45
	v_mov_b32_e32 v44, v46
	v_mov_b32_e32 v45, v50
	v_mov_b32_e32 v50, v47
	s_waitcnt lgkmcnt(3)
	v_mov_b32_e32 v46, v52
	s_waitcnt lgkmcnt(2)
	v_mov_b32_e32 v47, v56
	v_mov_b32_e32 v56, v53
	v_mov_b32_e32 v52, v54
	v_mov_b32_e32 v53, v58
	v_mov_b32_e32 v58, v55
	s_waitcnt lgkmcnt(1)
	v_mov_b32_e32 v54, v60
	s_waitcnt lgkmcnt(0)
	v_mov_b32_e32 v55, v64
	v_mov_b32_e32 v64, v61
	v_mov_b32_e32 v60, v62
	v_mov_b32_e32 v61, v66
	s_add_i32 s28, s28, 32
	v_mov_b32_e32 v66, v63
	v_pk_fma_f32 v[12:13], v[74:75], v[84:85], v[12:13] op_sel_hi:[0,1,1]
	v_pk_fma_f32 v[14:15], v[74:75], v[38:39], v[14:15] op_sel_hi:[0,1,1]
	v_pk_fma_f32 v[12:13], v[70:71], v[40:41], v[12:13] op_sel_hi:[0,1,1]
	v_pk_fma_f32 v[14:15], v[70:71], v[48:49], v[14:15] op_sel_hi:[0,1,1]
	v_pk_fma_f32 v[12:13], v[72:73], v[36:37], v[12:13] op_sel_hi:[0,1,1]
	v_pk_fma_f32 v[14:15], v[72:73], v[44:45], v[14:15] op_sel_hi:[0,1,1]
	v_pk_fma_f32 v[12:13], v[76:77], v[42:43], v[12:13] op_sel_hi:[0,1,1]
	v_pk_fma_f32 v[14:15], v[76:77], v[50:51], v[14:15] op_sel_hi:[0,1,1]
	v_pk_fma_f32 v[12:13], v[68:69], v[46:47], v[12:13] op_sel_hi:[0,1,1]
	v_pk_fma_f32 v[14:15], v[68:69], v[54:55], v[14:15] op_sel_hi:[0,1,1]
	v_pk_fma_f32 v[12:13], v[78:79], v[56:57], v[12:13] op_sel_hi:[0,1,1]
	v_pk_fma_f32 v[14:15], v[78:79], v[64:65], v[14:15] op_sel_hi:[0,1,1]
	v_pk_fma_f32 v[12:13], v[80:81], v[52:53], v[12:13] op_sel_hi:[0,1,1]
	v_pk_fma_f32 v[14:15], v[80:81], v[60:61], v[14:15] op_sel_hi:[0,1,1]
	v_pk_fma_f32 v[12:13], v[82:83], v[58:59], v[12:13] op_sel_hi:[0,1,1]
	v_pk_fma_f32 v[14:15], v[82:83], v[66:67], v[14:15] op_sel_hi:[0,1,1]
	global_load_dword v216, v86, s[4:5]
	s_add_u32 s4, s4, 0x3000
	s_addc_u32 s5, s5, 0
	global_load_dword v217, v86, s[4:5]
	s_add_u32 s4, s4, 0x3000
	s_addc_u32 s5, s5, 0
	global_load_dword v218, v86, s[4:5]
	s_add_u32 s4, s4, 0x3000
	s_addc_u32 s5, s5, 0
	global_load_dword v219, v86, s[4:5]
	s_add_u32 s4, s4, 0x3000
	s_addc_u32 s5, s5, 0
	global_load_dword v220, v86, s[4:5]
	s_add_u32 s4, s4, 0x3000
	s_addc_u32 s5, s5, 0
	global_load_dword v221, v86, s[4:5]
	s_add_u32 s4, s4, 0x3000
	s_addc_u32 s5, s5, 0
	global_load_dword v222, v86, s[4:5]
	s_add_u32 s4, s4, 0x3000
	s_addc_u32 s5, s5, 0
	global_load_dword v223, v86, s[4:5]
	s_add_u32 s4, s4, 0x3000
	s_addc_u32 s5, s5, 0
	s_waitcnt vmcnt(56)
	v_mov_b32_e32 v74, v156
	v_mov_b32_e32 v70, v157
	v_mov_b32_e32 v72, v158
	v_mov_b32_e32 v76, v159
	v_mov_b32_e32 v68, v164
	v_mov_b32_e32 v78, v165
	v_mov_b32_e32 v80, v166
	v_mov_b32_e32 v82, v167
	v_add_u32_e32 v36, s28, v19
	v_add_u32_e32 v37, 0x11000, v36
	v_add_u32_e32 v40, 0x12000, v36
	v_add_u32_e32 v44, 0x13000, v36
	v_add_u32_e32 v48, 0x14000, v36
	v_add_u32_e32 v52, 0x11010, v36
	v_add_u32_e32 v56, 0x12010, v36
	v_add_u32_e32 v60, 0x13010, v36
	v_add_u32_e32 v64, 0x14010, v36
	ds_read_b128 v[36:39], v37
	ds_read_b128 v[40:43], v40
	ds_read_b128 v[44:47], v44
	ds_read_b128 v[48:51], v48
	ds_read_b128 v[52:55], v52
	ds_read_b128 v[56:59], v56
	ds_read_b128 v[60:63], v60
	ds_read_b128 v[64:67], v64
	s_waitcnt lgkmcnt(7)
	v_mov_b32_e32 v84, v36
	s_waitcnt lgkmcnt(6)
	v_mov_b32_e32 v85, v40
	v_mov_b32_e32 v40, v37
	v_mov_b32_e32 v36, v38
	v_mov_b32_e32 v37, v42
	v_mov_b32_e32 v42, v39
	s_waitcnt lgkmcnt(5)
	v_mov_b32_e32 v38, v44
	s_waitcnt lgkmcnt(4)
	v_mov_b32_e32 v39, v48
	v_mov_b32_e32 v48, v45
	v_mov_b32_e32 v44, v46
	v_mov_b32_e32 v45, v50
	v_mov_b32_e32 v50, v47
	s_waitcnt lgkmcnt(3)
	v_mov_b32_e32 v46, v52
	s_waitcnt lgkmcnt(2)
	v_mov_b32_e32 v47, v56
	v_mov_b32_e32 v56, v53
	v_mov_b32_e32 v52, v54
	v_mov_b32_e32 v53, v58
	v_mov_b32_e32 v58, v55
	s_waitcnt lgkmcnt(1)
	v_mov_b32_e32 v54, v60
	s_waitcnt lgkmcnt(0)
; DI void phase0(const Params& p, unsigned char* shm, int tid) {
;     ...
;       for (int k = 0; k < 128; ++k) {
;         const float w = wp[(size_t)k * 3072]; const int kk = kc * 128 + k;
;         a0 += ssc[kk] * w; a1 += ssc[1024 + kk] * w; a2 += ssc[2048 + kk] * w; a3 += ssc[3072 + kk] * w;
;       }
	v_mov_b32_e32 v55, v64
	v_mov_b32_e32 v64, v61
	v_mov_b32_e32 v60, v62
	v_mov_b32_e32 v61, v66
	s_add_i32 s28, s28, 32
	v_mov_b32_e32 v66, v63
	v_pk_fma_f32 v[12:13], v[74:75], v[84:85], v[12:13] op_sel_hi:[0,1,1]
	v_pk_fma_f32 v[14:15], v[74:75], v[38:39], v[14:15] op_sel_hi:[0,1,1]
	v_pk_fma_f32 v[12:13], v[70:71], v[40:41], v[12:13] op_sel_hi:[0,1,1]
	v_pk_fma_f32 v[14:15], v[70:71], v[48:49], v[14:15] op_sel_hi:[0,1,1]
	v_pk_fma_f32 v[12:13], v[72:73], v[36:37], v[12:13] op_sel_hi:[0,1,1]
	v_pk_fma_f32 v[14:15], v[72:73], v[44:45], v[14:15] op_sel_hi:[0,1,1]
	v_pk_fma_f32 v[12:13], v[76:77], v[42:43], v[12:13] op_sel_hi:[0,1,1]
	v_pk_fma_f32 v[14:15], v[76:77], v[50:51], v[14:15] op_sel_hi:[0,1,1]
	v_pk_fma_f32 v[12:13], v[68:69], v[46:47], v[12:13] op_sel_hi:[0,1,1]
	v_pk_fma_f32 v[14:15], v[68:69], v[54:55], v[14:15] op_sel_hi:[0,1,1]
	v_pk_fma_f32 v[12:13], v[78:79], v[56:57], v[12:13] op_sel_hi:[0,1,1]
	v_pk_fma_f32 v[14:15], v[78:79], v[64:65], v[14:15] op_sel_hi:[0,1,1]
	v_pk_fma_f32 v[12:13], v[80:81], v[52:53], v[12:13] op_sel_hi:[0,1,1]
	v_pk_fma_f32 v[14:15], v[80:81], v[60:61], v[14:15] op_sel_hi:[0,1,1]
	v_pk_fma_f32 v[12:13], v[82:83], v[58:59], v[12:13] op_sel_hi:[0,1,1]
	v_pk_fma_f32 v[14:15], v[82:83], v[66:67], v[14:15] op_sel_hi:[0,1,1]
	global_load_dword v224, v86, s[4:5]
	s_add_u32 s4, s4, 0x3000
	s_addc_u32 s5, s5, 0
	global_load_dword v225, v86, s[4:5]
	s_add_u32 s4, s4, 0x3000
	s_addc_u32 s5, s5, 0
	global_load_dword v226, v86, s[4:5]
	s_add_u32 s4, s4, 0x3000
	s_addc_u32 s5, s5, 0
	global_load_dword v227, v86, s[4:5]
	s_add_u32 s4, s4, 0x3000
	s_addc_u32 s5, s5, 0
	global_load_dword v228, v86, s[4:5]
	s_add_u32 s4, s4, 0x3000
	s_addc_u32 s5, s5, 0
	global_load_dword v229, v86, s[4:5]
	s_add_u32 s4, s4, 0x3000
	s_addc_u32 s5, s5, 0
	global_load_dword v230, v86, s[4:5]
	s_add_u32 s4, s4, 0x3000
	s_addc_u32 s5, s5, 0
	global_load_dword v231, v86, s[4:5]
	s_add_u32 s4, s4, 0x3000
	s_addc_u32 s5, s5, 0
	s_waitcnt vmcnt(56)
	v_mov_b32_e32 v74, v168
	v_mov_b32_e32 v70, v169
	v_mov_b32_e32 v72, v170
	v_mov_b32_e32 v76, v171
	v_mov_b32_e32 v68, v172
	v_mov_b32_e32 v78, v173
	v_mov_b32_e32 v80, v174
	v_mov_b32_e32 v82, v175
	v_add_u32_e32 v36, s28, v19
	v_add_u32_e32 v37, 0x11000, v36
	v_add_u32_e32 v40, 0x12000, v36
	v_add_u32_e32 v44, 0x13000, v36
	v_add_u32_e32 v48, 0x14000, v36
	v_add_u32_e32 v52, 0x11010, v36
	v_add_u32_e32 v56, 0x12010, v36
	v_add_u32_e32 v60, 0x13010, v36
	v_add_u32_e32 v64, 0x14010, v36
	ds_read_b128 v[36:39], v37
	ds_read_b128 v[40:43], v40
	ds_read_b128 v[44:47], v44
	ds_read_b128 v[48:51], v48
	ds_read_b128 v[52:55], v52
	ds_read_b128 v[56:59], v56
	ds_read_b128 v[60:63], v60
	ds_read_b128 v[64:67], v64
	s_waitcnt lgkmcnt(7)
	v_mov_b32_e32 v84, v36
	s_waitcnt lgkmcnt(6)
	v_mov_b32_e32 v85, v40
	v_mov_b32_e32 v40, v37
	v_mov_b32_e32 v36, v38
	v_mov_b32_e32 v37, v42
	v_mov_b32_e32 v42, v39
	s_waitcnt lgkmcnt(5)
	v_mov_b32_e32 v38, v44
	s_waitcnt lgkmcnt(4)
	v_mov_b32_e32 v39, v48
	v_mov_b32_e32 v48, v45
	v_mov_b32_e32 v44, v46
	v_mov_b32_e32 v45, v50
	v_mov_b32_e32 v50, v47
	s_waitcnt lgkmcnt(3)
	v_mov_b32_e32 v46, v52
	s_waitcnt lgkmcnt(2)
	v_mov_b32_e32 v47, v56
	v_mov_b32_e32 v56, v53
	v_mov_b32_e32 v52, v54
	v_mov_b32_e32 v53, v58
	v_mov_b32_e32 v58, v55
	s_waitcnt lgkmcnt(1)
	v_mov_b32_e32 v54, v60
	s_waitcnt lgkmcnt(0)
	v_mov_b32_e32 v55, v64
	v_mov_b32_e32 v64, v61
	v_mov_b32_e32 v60, v62
	v_mov_b32_e32 v61, v66
	s_add_i32 s28, s28, 32
	v_mov_b32_e32 v66, v63
	v_pk_fma_f32 v[12:13], v[74:75], v[84:85], v[12:13] op_sel_hi:[0,1,1]
	v_pk_fma_f32 v[14:15], v[74:75], v[38:39], v[14:15] op_sel_hi:[0,1,1]
	v_pk_fma_f32 v[12:13], v[70:71], v[40:41], v[12:13] op_sel_hi:[0,1,1]
	v_pk_fma_f32 v[14:15], v[70:71], v[48:49], v[14:15] op_sel_hi:[0,1,1]
	v_pk_fma_f32 v[12:13], v[72:73], v[36:37], v[12:13] op_sel_hi:[0,1,1]
	v_pk_fma_f32 v[14:15], v[72:73], v[44:45], v[14:15] op_sel_hi:[0,1,1]
	v_pk_fma_f32 v[12:13], v[76:77], v[42:43], v[12:13] op_sel_hi:[0,1,1]
	v_pk_fma_f32 v[14:15], v[76:77], v[50:51], v[14:15] op_sel_hi:[0,1,1]
	v_pk_fma_f32 v[12:13], v[68:69], v[46:47], v[12:13] op_sel_hi:[0,1,1]
	v_pk_fma_f32 v[14:15], v[68:69], v[54:55], v[14:15] op_sel_hi:[0,1,1]
	v_pk_fma_f32 v[12:13], v[78:79], v[56:57], v[12:13] op_sel_hi:[0,1,1]
	v_pk_fma_f32 v[14:15], v[78:79], v[64:65], v[14:15] op_sel_hi:[0,1,1]
	v_pk_fma_f32 v[12:13], v[80:81], v[52:53], v[12:13] op_sel_hi:[0,1,1]
	v_pk_fma_f32 v[14:15], v[80:81], v[60:61], v[14:15] op_sel_hi:[0,1,1]
	v_pk_fma_f32 v[12:13], v[82:83], v[58:59], v[12:13] op_sel_hi:[0,1,1]
	v_pk_fma_f32 v[14:15], v[82:83], v[66:67], v[14:15] op_sel_hi:[0,1,1]
	s_waitcnt vmcnt(48)
	v_mov_b32_e32 v74, v176
	v_mov_b32_e32 v70, v177
	v_mov_b32_e32 v72, v178
	v_mov_b32_e32 v76, v179
	v_mov_b32_e32 v68, v180
	v_mov_b32_e32 v78, v181
	v_mov_b32_e32 v80, v182
	v_mov_b32_e32 v82, v183
	v_add_u32_e32 v36, s28, v19
	v_add_u32_e32 v37, 0x11000, v36
	v_add_u32_e32 v40, 0x12000, v36
	v_add_u32_e32 v44, 0x13000, v36
	v_add_u32_e32 v48, 0x14000, v36
	v_add_u32_e32 v52, 0x11010, v36
	v_add_u32_e32 v56, 0x12010, v36
	v_add_u32_e32 v60, 0x13010, v36
	v_add_u32_e32 v64, 0x14010, v36
	ds_read_b128 v[36:39], v37
	ds_read_b128 v[40:43], v40
	ds_read_b128 v[44:47], v44
	ds_read_b128 v[48:51], v48
	ds_read_b128 v[52:55], v52
	ds_read_b128 v[56:59], v56
	ds_read_b128 v[60:63], v60
	ds_read_b128 v[64:67], v64
	s_waitcnt lgkmcnt(7)
	v_mov_b32_e32 v84, v36
	s_waitcnt lgkmcnt(6)
	v_mov_b32_e32 v85, v40
	v_mov_b32_e32 v40, v37
	v_mov_b32_e32 v36, v38
	v_mov_b32_e32 v37, v42
	v_mov_b32_e32 v42, v39
	s_waitcnt lgkmcnt(5)
	v_mov_b32_e32 v38, v44
	s_waitcnt lgkmcnt(4)
; DI void phase0(const Params& p, unsigned char* shm, int tid) {
;     ...
;       for (int k = 0; k < 128; ++k) {
;         const float w = wp[(size_t)k * 3072]; const int kk = kc * 128 + k;
;         a0 += ssc[kk] * w; a1 += ssc[1024 + kk] * w; a2 += ssc[2048 + kk] * w; a3 += ssc[3072 + kk] * w;
;       }
	v_mov_b32_e32 v39, v48
	v_mov_b32_e32 v48, v45
	v_mov_b32_e32 v44, v46
	v_mov_b32_e32 v45, v50
	v_mov_b32_e32 v50, v47
	s_waitcnt lgkmcnt(3)
	v_mov_b32_e32 v46, v52
	s_waitcnt lgkmcnt(2)
	v_mov_b32_e32 v47, v56
	v_mov_b32_e32 v56, v53
	v_mov_b32_e32 v52, v54
	v_mov_b32_e32 v53, v58
	v_mov_b32_e32 v58, v55
	s_waitcnt lgkmcnt(1)
	v_mov_b32_e32 v54, v60
	s_waitcnt lgkmcnt(0)
	v_mov_b32_e32 v55, v64
	v_mov_b32_e32 v64, v61
	v_mov_b32_e32 v60, v62
	v_mov_b32_e32 v61, v66
	s_add_i32 s28, s28, 32
	v_mov_b32_e32 v66, v63
	v_pk_fma_f32 v[12:13], v[74:75], v[84:85], v[12:13] op_sel_hi:[0,1,1]
	v_pk_fma_f32 v[14:15], v[74:75], v[38:39], v[14:15] op_sel_hi:[0,1,1]
	v_pk_fma_f32 v[12:13], v[70:71], v[40:41], v[12:13] op_sel_hi:[0,1,1]
	v_pk_fma_f32 v[14:15], v[70:71], v[48:49], v[14:15] op_sel_hi:[0,1,1]
	v_pk_fma_f32 v[12:13], v[72:73], v[36:37], v[12:13] op_sel_hi:[0,1,1]
	v_pk_fma_f32 v[14:15], v[72:73], v[44:45], v[14:15] op_sel_hi:[0,1,1]
	v_pk_fma_f32 v[12:13], v[76:77], v[42:43], v[12:13] op_sel_hi:[0,1,1]
	v_pk_fma_f32 v[14:15], v[76:77], v[50:51], v[14:15] op_sel_hi:[0,1,1]
	v_pk_fma_f32 v[12:13], v[68:69], v[46:47], v[12:13] op_sel_hi:[0,1,1]
	v_pk_fma_f32 v[14:15], v[68:69], v[54:55], v[14:15] op_sel_hi:[0,1,1]
	v_pk_fma_f32 v[12:13], v[78:79], v[56:57], v[12:13] op_sel_hi:[0,1,1]
	v_pk_fma_f32 v[14:15], v[78:79], v[64:65], v[14:15] op_sel_hi:[0,1,1]
	v_pk_fma_f32 v[12:13], v[80:81], v[52:53], v[12:13] op_sel_hi:[0,1,1]
	v_pk_fma_f32 v[14:15], v[80:81], v[60:61], v[14:15] op_sel_hi:[0,1,1]
	v_pk_fma_f32 v[12:13], v[82:83], v[58:59], v[12:13] op_sel_hi:[0,1,1]
	v_pk_fma_f32 v[14:15], v[82:83], v[66:67], v[14:15] op_sel_hi:[0,1,1]
	s_waitcnt vmcnt(40)
	v_mov_b32_e32 v74, v184
	v_mov_b32_e32 v70, v185
	v_mov_b32_e32 v72, v186
	v_mov_b32_e32 v76, v187
	v_mov_b32_e32 v68, v188
	v_mov_b32_e32 v78, v189
	v_mov_b32_e32 v80, v190
	v_mov_b32_e32 v82, v191
	v_add_u32_e32 v36, s28, v19
	v_add_u32_e32 v37, 0x11000, v36
	v_add_u32_e32 v40, 0x12000, v36
	v_add_u32_e32 v44, 0x13000, v36
	v_add_u32_e32 v48, 0x14000, v36
	v_add_u32_e32 v52, 0x11010, v36
	v_add_u32_e32 v56, 0x12010, v36
	v_add_u32_e32 v60, 0x13010, v36
	v_add_u32_e32 v64, 0x14010, v36
	ds_read_b128 v[36:39], v37
	ds_read_b128 v[40:43], v40
	ds_read_b128 v[44:47], v44
	ds_read_b128 v[48:51], v48
	ds_read_b128 v[52:55], v52
	ds_read_b128 v[56:59], v56
	ds_read_b128 v[60:63], v60
	ds_read_b128 v[64:67], v64
	s_waitcnt lgkmcnt(7)
	v_mov_b32_e32 v84, v36
	s_waitcnt lgkmcnt(6)
	v_mov_b32_e32 v85, v40
	v_mov_b32_e32 v40, v37
	v_mov_b32_e32 v36, v38
	v_mov_b32_e32 v37, v42
	v_mov_b32_e32 v42, v39
	s_waitcnt lgkmcnt(5)
	v_mov_b32_e32 v38, v44
	s_waitcnt lgkmcnt(4)
	v_mov_b32_e32 v39, v48
	v_mov_b32_e32 v48, v45
	v_mov_b32_e32 v44, v46
	v_mov_b32_e32 v45, v50
	v_mov_b32_e32 v50, v47
	s_waitcnt lgkmcnt(3)
	v_mov_b32_e32 v46, v52
	s_waitcnt lgkmcnt(2)
	v_mov_b32_e32 v47, v56
	v_mov_b32_e32 v56, v53
	v_mov_b32_e32 v52, v54
	v_mov_b32_e32 v53, v58
	v_mov_b32_e32 v58, v55
	s_waitcnt lgkmcnt(1)
	v_mov_b32_e32 v54, v60
	s_waitcnt lgkmcnt(0)
	v_mov_b32_e32 v55, v64
	v_mov_b32_e32 v64, v61
	v_mov_b32_e32 v60, v62
	v_mov_b32_e32 v61, v66
	s_add_i32 s28, s28, 32
	v_mov_b32_e32 v66, v63
	v_pk_fma_f32 v[12:13], v[74:75], v[84:85], v[12:13] op_sel_hi:[0,1,1]
	v_pk_fma_f32 v[14:15], v[74:75], v[38:39], v[14:15] op_sel_hi:[0,1,1]
	v_pk_fma_f32 v[12:13], v[70:71], v[40:41], v[12:13] op_sel_hi:[0,1,1]
	v_pk_fma_f32 v[14:15], v[70:71], v[48:49], v[14:15] op_sel_hi:[0,1,1]
	v_pk_fma_f32 v[12:13], v[72:73], v[36:37], v[12:13] op_sel_hi:[0,1,1]
	v_pk_fma_f32 v[14:15], v[72:73], v[44:45], v[14:15] op_sel_hi:[0,1,1]
	v_pk_fma_f32 v[12:13], v[76:77], v[42:43], v[12:13] op_sel_hi:[0,1,1]
	v_pk_fma_f32 v[14:15], v[76:77], v[50:51], v[14:15] op_sel_hi:[0,1,1]
	v_pk_fma_f32 v[12:13], v[68:69], v[46:47], v[12:13] op_sel_hi:[0,1,1]
	v_pk_fma_f32 v[14:15], v[68:69], v[54:55], v[14:15] op_sel_hi:[0,1,1]
	v_pk_fma_f32 v[12:13], v[78:79], v[56:57], v[12:13] op_sel_hi:[0,1,1]
	v_pk_fma_f32 v[14:15], v[78:79], v[64:65], v[14:15] op_sel_hi:[0,1,1]
	v_pk_fma_f32 v[12:13], v[80:81], v[52:53], v[12:13] op_sel_hi:[0,1,1]
	v_pk_fma_f32 v[14:15], v[80:81], v[60:61], v[14:15] op_sel_hi:[0,1,1]
	v_pk_fma_f32 v[12:13], v[82:83], v[58:59], v[12:13] op_sel_hi:[0,1,1]
	v_pk_fma_f32 v[14:15], v[82:83], v[66:67], v[14:15] op_sel_hi:[0,1,1]
	s_waitcnt vmcnt(32)
	v_mov_b32_e32 v74, v192
	v_mov_b32_e32 v70, v193
	v_mov_b32_e32 v72, v194
	v_mov_b32_e32 v76, v195
	v_mov_b32_e32 v68, v196
	v_mov_b32_e32 v78, v197
	v_mov_b32_e32 v80, v198
	v_mov_b32_e32 v82, v199
	v_add_u32_e32 v36, s28, v19
	v_add_u32_e32 v37, 0x11000, v36
	v_add_u32_e32 v40, 0x12000, v36
	v_add_u32_e32 v44, 0x13000, v36
	v_add_u32_e32 v48, 0x14000, v36
	v_add_u32_e32 v52, 0x11010, v36
	v_add_u32_e32 v56, 0x12010, v36
	v_add_u32_e32 v60, 0x13010, v36
	v_add_u32_e32 v64, 0x14010, v36
	ds_read_b128 v[36:39], v37
	ds_read_b128 v[40:43], v40
	ds_read_b128 v[44:47], v44
	ds_read_b128 v[48:51], v48
	ds_read_b128 v[52:55], v52
	ds_read_b128 v[56:59], v56
	ds_read_b128 v[60:63], v60
	ds_read_b128 v[64:67], v64
	s_waitcnt lgkmcnt(7)
	v_mov_b32_e32 v84, v36
	s_waitcnt lgkmcnt(6)
	v_mov_b32_e32 v85, v40
	v_mov_b32_e32 v40, v37
	v_mov_b32_e32 v36, v38
	v_mov_b32_e32 v37, v42
	v_mov_b32_e32 v42, v39
	s_waitcnt lgkmcnt(5)
	v_mov_b32_e32 v38, v44
	s_waitcnt lgkmcnt(4)
	v_mov_b32_e32 v39, v48
	v_mov_b32_e32 v48, v45
	v_mov_b32_e32 v44, v46
	v_mov_b32_e32 v45, v50
	v_mov_b32_e32 v50, v47
	s_waitcnt lgkmcnt(3)
	v_mov_b32_e32 v46, v52
	s_waitcnt lgkmcnt(2)
	v_mov_b32_e32 v47, v56
	v_mov_b32_e32 v56, v53
	v_mov_b32_e32 v52, v54
	v_mov_b32_e32 v53, v58
	v_mov_b32_e32 v58, v55
	s_waitcnt lgkmcnt(1)
; DI void phase0(const Params& p, unsigned char* shm, int tid) {
;     ...
;       for (int k = 0; k < 128; ++k) {
;         const float w = wp[(size_t)k * 3072]; const int kk = kc * 128 + k;
;         a0 += ssc[kk] * w; a1 += ssc[1024 + kk] * w; a2 += ssc[2048 + kk] * w; a3 += ssc[3072 + kk] * w;
;       }
	v_mov_b32_e32 v54, v60
	s_waitcnt lgkmcnt(0)
	v_mov_b32_e32 v55, v64
	v_mov_b32_e32 v64, v61
	v_mov_b32_e32 v60, v62
	v_mov_b32_e32 v61, v66
	s_add_i32 s28, s28, 32
	v_mov_b32_e32 v66, v63
	v_pk_fma_f32 v[12:13], v[74:75], v[84:85], v[12:13] op_sel_hi:[0,1,1]
	v_pk_fma_f32 v[14:15], v[74:75], v[38:39], v[14:15] op_sel_hi:[0,1,1]
	v_pk_fma_f32 v[12:13], v[70:71], v[40:41], v[12:13] op_sel_hi:[0,1,1]
	v_pk_fma_f32 v[14:15], v[70:71], v[48:49], v[14:15] op_sel_hi:[0,1,1]
	v_pk_fma_f32 v[12:13], v[72:73], v[36:37], v[12:13] op_sel_hi:[0,1,1]
	v_pk_fma_f32 v[14:15], v[72:73], v[44:45], v[14:15] op_sel_hi:[0,1,1]
	v_pk_fma_f32 v[12:13], v[76:77], v[42:43], v[12:13] op_sel_hi:[0,1,1]
	v_pk_fma_f32 v[14:15], v[76:77], v[50:51], v[14:15] op_sel_hi:[0,1,1]
	v_pk_fma_f32 v[12:13], v[68:69], v[46:47], v[12:13] op_sel_hi:[0,1,1]
	v_pk_fma_f32 v[14:15], v[68:69], v[54:55], v[14:15] op_sel_hi:[0,1,1]
	v_pk_fma_f32 v[12:13], v[78:79], v[56:57], v[12:13] op_sel_hi:[0,1,1]
	v_pk_fma_f32 v[14:15], v[78:79], v[64:65], v[14:15] op_sel_hi:[0,1,1]
	v_pk_fma_f32 v[12:13], v[80:81], v[52:53], v[12:13] op_sel_hi:[0,1,1]
	v_pk_fma_f32 v[14:15], v[80:81], v[60:61], v[14:15] op_sel_hi:[0,1,1]
	v_pk_fma_f32 v[12:13], v[82:83], v[58:59], v[12:13] op_sel_hi:[0,1,1]
	v_pk_fma_f32 v[14:15], v[82:83], v[66:67], v[14:15] op_sel_hi:[0,1,1]
	s_waitcnt vmcnt(24)
	v_mov_b32_e32 v74, v200
	v_mov_b32_e32 v70, v201
	v_mov_b32_e32 v72, v202
	v_mov_b32_e32 v76, v203
	v_mov_b32_e32 v68, v204
	v_mov_b32_e32 v78, v205
	v_mov_b32_e32 v80, v206
	v_mov_b32_e32 v82, v207
	v_add_u32_e32 v36, s28, v19
	v_add_u32_e32 v37, 0x11000, v36
	v_add_u32_e32 v40, 0x12000, v36
	v_add_u32_e32 v44, 0x13000, v36
	v_add_u32_e32 v48, 0x14000, v36
	v_add_u32_e32 v52, 0x11010, v36
	v_add_u32_e32 v56, 0x12010, v36
	v_add_u32_e32 v60, 0x13010, v36
	v_add_u32_e32 v64, 0x14010, v36
	ds_read_b128 v[36:39], v37
	ds_read_b128 v[40:43], v40
	ds_read_b128 v[44:47], v44
	ds_read_b128 v[48:51], v48
	ds_read_b128 v[52:55], v52
	ds_read_b128 v[56:59], v56
	ds_read_b128 v[60:63], v60
	ds_read_b128 v[64:67], v64
	s_waitcnt lgkmcnt(7)
	v_mov_b32_e32 v84, v36
	s_waitcnt lgkmcnt(6)
	v_mov_b32_e32 v85, v40
	v_mov_b32_e32 v40, v37
	v_mov_b32_e32 v36, v38
	v_mov_b32_e32 v37, v42
	v_mov_b32_e32 v42, v39
	s_waitcnt lgkmcnt(5)
	v_mov_b32_e32 v38, v44
	s_waitcnt lgkmcnt(4)
	v_mov_b32_e32 v39, v48
	v_mov_b32_e32 v48, v45
	v_mov_b32_e32 v44, v46
	v_mov_b32_e32 v45, v50
	v_mov_b32_e32 v50, v47
	s_waitcnt lgkmcnt(3)
	v_mov_b32_e32 v46, v52
	s_waitcnt lgkmcnt(2)
	v_mov_b32_e32 v47, v56
	v_mov_b32_e32 v56, v53
	v_mov_b32_e32 v52, v54
	v_mov_b32_e32 v53, v58
	v_mov_b32_e32 v58, v55
	s_waitcnt lgkmcnt(1)
	v_mov_b32_e32 v54, v60
	s_waitcnt lgkmcnt(0)
	v_mov_b32_e32 v55, v64
	v_mov_b32_e32 v64, v61
	v_mov_b32_e32 v60, v62
	v_mov_b32_e32 v61, v66
	s_add_i32 s28, s28, 32
	v_mov_b32_e32 v66, v63
	v_pk_fma_f32 v[12:13], v[74:75], v[84:85], v[12:13] op_sel_hi:[0,1,1]
	v_pk_fma_f32 v[14:15], v[74:75], v[38:39], v[14:15] op_sel_hi:[0,1,1]
	v_pk_fma_f32 v[12:13], v[70:71], v[40:41], v[12:13] op_sel_hi:[0,1,1]
	v_pk_fma_f32 v[14:15], v[70:71], v[48:49], v[14:15] op_sel_hi:[0,1,1]
	v_pk_fma_f32 v[12:13], v[72:73], v[36:37], v[12:13] op_sel_hi:[0,1,1]
	v_pk_fma_f32 v[14:15], v[72:73], v[44:45], v[14:15] op_sel_hi:[0,1,1]
	v_pk_fma_f32 v[12:13], v[76:77], v[42:43], v[12:13] op_sel_hi:[0,1,1]
	v_pk_fma_f32 v[14:15], v[76:77], v[50:51], v[14:15] op_sel_hi:[0,1,1]
	v_pk_fma_f32 v[12:13], v[68:69], v[46:47], v[12:13] op_sel_hi:[0,1,1]
	v_pk_fma_f32 v[14:15], v[68:69], v[54:55], v[14:15] op_sel_hi:[0,1,1]
	v_pk_fma_f32 v[12:13], v[78:79], v[56:57], v[12:13] op_sel_hi:[0,1,1]
	v_pk_fma_f32 v[14:15], v[78:79], v[64:65], v[14:15] op_sel_hi:[0,1,1]
	v_pk_fma_f32 v[12:13], v[80:81], v[52:53], v[12:13] op_sel_hi:[0,1,1]
	v_pk_fma_f32 v[14:15], v[80:81], v[60:61], v[14:15] op_sel_hi:[0,1,1]
	v_pk_fma_f32 v[12:13], v[82:83], v[58:59], v[12:13] op_sel_hi:[0,1,1]
	v_pk_fma_f32 v[14:15], v[82:83], v[66:67], v[14:15] op_sel_hi:[0,1,1]
	s_waitcnt vmcnt(16)
	v_mov_b32_e32 v74, v208
	v_mov_b32_e32 v70, v209
	v_mov_b32_e32 v72, v210
	v_mov_b32_e32 v76, v211
	v_mov_b32_e32 v68, v212
	v_mov_b32_e32 v78, v213
	v_mov_b32_e32 v80, v214
	v_mov_b32_e32 v82, v215
	v_add_u32_e32 v36, s28, v19
	v_add_u32_e32 v37, 0x11000, v36
	v_add_u32_e32 v40, 0x12000, v36
	v_add_u32_e32 v44, 0x13000, v36
	v_add_u32_e32 v48, 0x14000, v36
	v_add_u32_e32 v52, 0x11010, v36
	v_add_u32_e32 v56, 0x12010, v36
	v_add_u32_e32 v60, 0x13010, v36
	v_add_u32_e32 v64, 0x14010, v36
	ds_read_b128 v[36:39], v37
	ds_read_b128 v[40:43], v40
	ds_read_b128 v[44:47], v44
	ds_read_b128 v[48:51], v48
	ds_read_b128 v[52:55], v52
	ds_read_b128 v[56:59], v56
	ds_read_b128 v[60:63], v60
	ds_read_b128 v[64:67], v64
	s_waitcnt lgkmcnt(7)
	v_mov_b32_e32 v84, v36
	s_waitcnt lgkmcnt(6)
	v_mov_b32_e32 v85, v40
	v_mov_b32_e32 v40, v37
	v_mov_b32_e32 v36, v38
	v_mov_b32_e32 v37, v42
	v_mov_b32_e32 v42, v39
	s_waitcnt lgkmcnt(5)
	v_mov_b32_e32 v38, v44
	s_waitcnt lgkmcnt(4)
	v_mov_b32_e32 v39, v48
	v_mov_b32_e32 v48, v45
	v_mov_b32_e32 v44, v46
	v_mov_b32_e32 v45, v50
	v_mov_b32_e32 v50, v47
	s_waitcnt lgkmcnt(3)
	v_mov_b32_e32 v46, v52
	s_waitcnt lgkmcnt(2)
	v_mov_b32_e32 v47, v56
	v_mov_b32_e32 v56, v53
	v_mov_b32_e32 v52, v54
	v_mov_b32_e32 v53, v58
	v_mov_b32_e32 v58, v55
	s_waitcnt lgkmcnt(1)
	v_mov_b32_e32 v54, v60
	s_waitcnt lgkmcnt(0)
; DI void phase0(const Params& p, unsigned char* shm, int tid) {
;     ...
;       for (int k = 0; k < 128; ++k) {
;         const float w = wp[(size_t)k * 3072]; const int kk = kc * 128 + k;
;         a0 += ssc[kk] * w; a1 += ssc[1024 + kk] * w; a2 += ssc[2048 + kk] * w; a3 += ssc[3072 + kk] * w;
;       }
;       red[(kc * 4 + 0) * 64 + col] = a0; red[(kc * 4 + 1) * 64 + col] = a1; red[(kc * 4 + 2) * 64 + col] = a2; red[(kc * 4 + 3) * 64 + col] = a3;
	v_mov_b32_e32 v55, v64
	v_mov_b32_e32 v64, v61
	v_mov_b32_e32 v60, v62
	v_mov_b32_e32 v61, v66
	s_add_i32 s28, s28, 32
	v_mov_b32_e32 v66, v63
	v_pk_fma_f32 v[12:13], v[74:75], v[84:85], v[12:13] op_sel_hi:[0,1,1]
	v_pk_fma_f32 v[14:15], v[74:75], v[38:39], v[14:15] op_sel_hi:[0,1,1]
	v_pk_fma_f32 v[12:13], v[70:71], v[40:41], v[12:13] op_sel_hi:[0,1,1]
	v_pk_fma_f32 v[14:15], v[70:71], v[48:49], v[14:15] op_sel_hi:[0,1,1]
	v_pk_fma_f32 v[12:13], v[72:73], v[36:37], v[12:13] op_sel_hi:[0,1,1]
	v_pk_fma_f32 v[14:15], v[72:73], v[44:45], v[14:15] op_sel_hi:[0,1,1]
	v_pk_fma_f32 v[12:13], v[76:77], v[42:43], v[12:13] op_sel_hi:[0,1,1]
	v_pk_fma_f32 v[14:15], v[76:77], v[50:51], v[14:15] op_sel_hi:[0,1,1]
	v_pk_fma_f32 v[12:13], v[68:69], v[46:47], v[12:13] op_sel_hi:[0,1,1]
	v_pk_fma_f32 v[14:15], v[68:69], v[54:55], v[14:15] op_sel_hi:[0,1,1]
	v_pk_fma_f32 v[12:13], v[78:79], v[56:57], v[12:13] op_sel_hi:[0,1,1]
	v_pk_fma_f32 v[14:15], v[78:79], v[64:65], v[14:15] op_sel_hi:[0,1,1]
	v_pk_fma_f32 v[12:13], v[80:81], v[52:53], v[12:13] op_sel_hi:[0,1,1]
	v_pk_fma_f32 v[14:15], v[80:81], v[60:61], v[14:15] op_sel_hi:[0,1,1]
	v_pk_fma_f32 v[12:13], v[82:83], v[58:59], v[12:13] op_sel_hi:[0,1,1]
	v_pk_fma_f32 v[14:15], v[82:83], v[66:67], v[14:15] op_sel_hi:[0,1,1]
	s_waitcnt vmcnt(8)
	v_mov_b32_e32 v74, v216
	v_mov_b32_e32 v70, v217
	v_mov_b32_e32 v72, v218
	v_mov_b32_e32 v76, v219
	v_mov_b32_e32 v68, v220
	v_mov_b32_e32 v78, v221
	v_mov_b32_e32 v80, v222
	v_mov_b32_e32 v82, v223
	v_add_u32_e32 v36, s28, v19
	v_add_u32_e32 v37, 0x11000, v36
	v_add_u32_e32 v40, 0x12000, v36
	v_add_u32_e32 v44, 0x13000, v36
	v_add_u32_e32 v48, 0x14000, v36
	v_add_u32_e32 v52, 0x11010, v36
	v_add_u32_e32 v56, 0x12010, v36
	v_add_u32_e32 v60, 0x13010, v36
	v_add_u32_e32 v64, 0x14010, v36
	ds_read_b128 v[36:39], v37
	ds_read_b128 v[40:43], v40
	ds_read_b128 v[44:47], v44
	ds_read_b128 v[48:51], v48
	ds_read_b128 v[52:55], v52
	ds_read_b128 v[56:59], v56
	ds_read_b128 v[60:63], v60
	ds_read_b128 v[64:67], v64
	s_waitcnt lgkmcnt(7)
	v_mov_b32_e32 v84, v36
	s_waitcnt lgkmcnt(6)
	v_mov_b32_e32 v85, v40
	v_mov_b32_e32 v40, v37
	v_mov_b32_e32 v36, v38
	v_mov_b32_e32 v37, v42
	v_mov_b32_e32 v42, v39
	s_waitcnt lgkmcnt(5)
	v_mov_b32_e32 v38, v44
	s_waitcnt lgkmcnt(4)
	v_mov_b32_e32 v39, v48
	v_mov_b32_e32 v48, v45
	v_mov_b32_e32 v44, v46
	v_mov_b32_e32 v45, v50
	v_mov_b32_e32 v50, v47
	s_waitcnt lgkmcnt(3)
	v_mov_b32_e32 v46, v52
	s_waitcnt lgkmcnt(2)
	v_mov_b32_e32 v47, v56
	v_mov_b32_e32 v56, v53
	v_mov_b32_e32 v52, v54
	v_mov_b32_e32 v53, v58
	v_mov_b32_e32 v58, v55
	s_waitcnt lgkmcnt(1)
	v_mov_b32_e32 v54, v60
	s_waitcnt lgkmcnt(0)
	v_mov_b32_e32 v55, v64
	v_mov_b32_e32 v64, v61
	v_mov_b32_e32 v60, v62
	v_mov_b32_e32 v61, v66
	s_add_i32 s28, s28, 32
	v_mov_b32_e32 v66, v63
	v_pk_fma_f32 v[12:13], v[74:75], v[84:85], v[12:13] op_sel_hi:[0,1,1]
	v_pk_fma_f32 v[14:15], v[74:75], v[38:39], v[14:15] op_sel_hi:[0,1,1]
	v_pk_fma_f32 v[12:13], v[70:71], v[40:41], v[12:13] op_sel_hi:[0,1,1]
	v_pk_fma_f32 v[14:15], v[70:71], v[48:49], v[14:15] op_sel_hi:[0,1,1]
	v_pk_fma_f32 v[12:13], v[72:73], v[36:37], v[12:13] op_sel_hi:[0,1,1]
	v_pk_fma_f32 v[14:15], v[72:73], v[44:45], v[14:15] op_sel_hi:[0,1,1]
	v_pk_fma_f32 v[12:13], v[76:77], v[42:43], v[12:13] op_sel_hi:[0,1,1]
	v_pk_fma_f32 v[14:15], v[76:77], v[50:51], v[14:15] op_sel_hi:[0,1,1]
	v_pk_fma_f32 v[12:13], v[68:69], v[46:47], v[12:13] op_sel_hi:[0,1,1]
	v_pk_fma_f32 v[14:15], v[68:69], v[54:55], v[14:15] op_sel_hi:[0,1,1]
	v_pk_fma_f32 v[12:13], v[78:79], v[56:57], v[12:13] op_sel_hi:[0,1,1]
	v_pk_fma_f32 v[14:15], v[78:79], v[64:65], v[14:15] op_sel_hi:[0,1,1]
	v_pk_fma_f32 v[12:13], v[80:81], v[52:53], v[12:13] op_sel_hi:[0,1,1]
	v_pk_fma_f32 v[14:15], v[80:81], v[60:61], v[14:15] op_sel_hi:[0,1,1]
	v_pk_fma_f32 v[12:13], v[82:83], v[58:59], v[12:13] op_sel_hi:[0,1,1]
	v_pk_fma_f32 v[14:15], v[82:83], v[66:67], v[14:15] op_sel_hi:[0,1,1]
	s_waitcnt vmcnt(0)
	v_mov_b32_e32 v74, v224
	v_mov_b32_e32 v70, v225
	v_mov_b32_e32 v72, v226
	v_mov_b32_e32 v76, v227
	v_mov_b32_e32 v68, v228
	v_mov_b32_e32 v78, v229
	v_mov_b32_e32 v80, v230
	v_mov_b32_e32 v82, v231
	v_add_u32_e32 v36, s28, v19
	v_add_u32_e32 v37, 0x11000, v36
	v_add_u32_e32 v40, 0x12000, v36
	v_add_u32_e32 v44, 0x13000, v36
	v_add_u32_e32 v48, 0x14000, v36
	v_add_u32_e32 v52, 0x11010, v36
	v_add_u32_e32 v56, 0x12010, v36
	v_add_u32_e32 v60, 0x13010, v36
	v_add_u32_e32 v64, 0x14010, v36
	ds_read_b128 v[36:39], v37
	ds_read_b128 v[40:43], v40
	ds_read_b128 v[44:47], v44
	ds_read_b128 v[48:51], v48
	ds_read_b128 v[52:55], v52
	ds_read_b128 v[56:59], v56
	ds_read_b128 v[60:63], v60
	ds_read_b128 v[64:67], v64
	s_waitcnt lgkmcnt(7)
	v_mov_b32_e32 v84, v36
	s_waitcnt lgkmcnt(6)
	v_mov_b32_e32 v85, v40
	v_mov_b32_e32 v40, v37
	v_mov_b32_e32 v36, v38
	v_mov_b32_e32 v37, v42
	v_mov_b32_e32 v42, v39
	s_waitcnt lgkmcnt(5)
	v_mov_b32_e32 v38, v44
	s_waitcnt lgkmcnt(4)
	v_mov_b32_e32 v39, v48
	v_mov_b32_e32 v48, v45
	v_mov_b32_e32 v44, v46
	v_mov_b32_e32 v45, v50
	v_mov_b32_e32 v50, v47
	s_waitcnt lgkmcnt(3)
	v_mov_b32_e32 v46, v52
	s_waitcnt lgkmcnt(2)
	v_mov_b32_e32 v47, v56
	v_mov_b32_e32 v56, v53
	v_mov_b32_e32 v52, v54
	v_mov_b32_e32 v53, v58
	v_mov_b32_e32 v58, v55
	s_waitcnt lgkmcnt(1)
	v_mov_b32_e32 v54, v60
	s_waitcnt lgkmcnt(0)
	v_mov_b32_e32 v55, v64
	v_mov_b32_e32 v64, v61
	v_mov_b32_e32 v60, v62
	v_mov_b32_e32 v61, v66
	s_add_i32 s28, s28, 32
	v_mov_b32_e32 v66, v63
	v_pk_fma_f32 v[12:13], v[74:75], v[84:85], v[12:13] op_sel_hi:[0,1,1]
	v_pk_fma_f32 v[14:15], v[74:75], v[38:39], v[14:15] op_sel_hi:[0,1,1]
	v_pk_fma_f32 v[12:13], v[70:71], v[40:41], v[12:13] op_sel_hi:[0,1,1]
	v_pk_fma_f32 v[14:15], v[70:71], v[48:49], v[14:15] op_sel_hi:[0,1,1]
	v_pk_fma_f32 v[12:13], v[72:73], v[36:37], v[12:13] op_sel_hi:[0,1,1]
	v_pk_fma_f32 v[14:15], v[72:73], v[44:45], v[14:15] op_sel_hi:[0,1,1]
	v_pk_fma_f32 v[12:13], v[76:77], v[42:43], v[12:13] op_sel_hi:[0,1,1]
	v_pk_fma_f32 v[14:15], v[76:77], v[50:51], v[14:15] op_sel_hi:[0,1,1]
	v_pk_fma_f32 v[12:13], v[68:69], v[46:47], v[12:13] op_sel_hi:[0,1,1]
	v_pk_fma_f32 v[14:15], v[68:69], v[54:55], v[14:15] op_sel_hi:[0,1,1]
	v_pk_fma_f32 v[12:13], v[78:79], v[56:57], v[12:13] op_sel_hi:[0,1,1]
	v_pk_fma_f32 v[14:15], v[78:79], v[64:65], v[14:15] op_sel_hi:[0,1,1]
	v_pk_fma_f32 v[12:13], v[80:81], v[52:53], v[12:13] op_sel_hi:[0,1,1]
	v_pk_fma_f32 v[14:15], v[80:81], v[60:61], v[14:15] op_sel_hi:[0,1,1]
	v_pk_fma_f32 v[12:13], v[82:83], v[58:59], v[12:13] op_sel_hi:[0,1,1]
	v_pk_fma_f32 v[14:15], v[82:83], v[66:67], v[14:15] op_sel_hi:[0,1,1]
	ds_write2st64_b32 v17, v12, v13 offset1:1
	ds_write2st64_b32 v17, v14, v15 offset0:2 offset1:3
	s_waitcnt lgkmcnt(0)
	s_barrier
; DI void phase0(const Params& p, unsigned char* shm, int tid) {
;     ...
;       if (tid < 256) {
;         const int b = tid >> 6, cc = tid & 63; float s = 0.f;
; #pragma unroll
;         for (int q = 0; q < 8; ++q) s += red[(q * 4 + b) * 64 + cc];
;         mod[(size_t)(l * 4 + b) * 3072 + cgp * 64 + cc] = s + p.b_ada[l * 3072 + cgp * 64 + cc];
;       }
	s_and_saveexec_b64 s[4:5], s[0:1]
	s_cbranch_execz .LBB0_7
	s_mul_i32 s28, s6, 0xc00
	s_add_i32 s28, s28, s10
	v_or_b32_e32 v10, s28, v2
	v_readlane_b32 s40, v252, 2
	v_ashrrev_i32_e32 v11, 31, v10
	v_readlane_b32 s50, v252, 12
	v_readlane_b32 s51, v252, 13
	v_readlane_b32 s28, v252, 22
	v_readlane_b32 s29, v252, 23
	v_lshl_add_u64 v[10:11], v[10:11], 2, s[50:51]
	global_load_dword v42, v[10:11], off
	ds_read2st64_b32 v[10:11], v18 offset1:4
	ds_read2st64_b32 v[12:13], v18 offset0:8 offset1:12
	ds_read2st64_b32 v[14:15], v18 offset0:16 offset1:20
	ds_read2st64_b32 v[36:37], v18 offset0:24 offset1:28
	v_lshl_add_u32 v43, s6, 2, v3
	s_waitcnt lgkmcnt(3)
	v_add_f32_e32 v10, 0, v10
	v_add_f32_e32 v10, v10, v11
	s_waitcnt lgkmcnt(2)
	v_add_f32_e32 v10, v10, v12
	v_add_f32_e32 v10, v10, v13
	s_waitcnt lgkmcnt(1)
	v_add_f32_e32 v10, v10, v14
	v_mov_b64_e32 v[38:39], s[28:29]
	v_add_f32_e32 v10, v10, v15
	v_mad_i64_i32 v[38:39], s[28:29], v43, s12, v[38:39]
	s_waitcnt lgkmcnt(0)
	v_add_f32_e32 v10, v10, v36
	v_lshlrev_b32_e32 v40, 2, v2
	v_mov_b32_e32 v41, v7
	v_lshl_add_u64 v[38:39], s[10:11], 2, v[38:39]
	v_add_f32_e32 v10, v10, v37
	v_readlane_b32 s41, v252, 3
	v_readlane_b32 s42, v252, 4
	v_readlane_b32 s43, v252, 5
	v_readlane_b32 s44, v252, 6
	v_readlane_b32 s45, v252, 7
	v_readlane_b32 s46, v252, 8
	v_readlane_b32 s47, v252, 9
	v_readlane_b32 s48, v252, 10
	v_readlane_b32 s49, v252, 11
	v_readlane_b32 s52, v252, 14
	v_readlane_b32 s53, v252, 15
	v_readlane_b32 s54, v252, 16
	v_readlane_b32 s55, v252, 17
	s_waitcnt vmcnt(0)
	v_add_f32_e32 v12, v10, v42
	v_lshl_add_u64 v[10:11], v[38:39], 0, v[40:41]
	global_store_dword v[10:11], v12, off
	s_branch .LBB0_7
